# prep g-scale loads batched; thin_gemm loads batched; act_fixup body rewritten by hand (one thread per column group, 32 loads in flight, shared conv weights)
# speedup vs baseline: 1.0886x; 1.0170x over previous
; __device__ __forceinline__ u32x4 pack8(const float* f) { u32x4 w; w.x = pk2(f[0], f[1]); w.y = pk2(f[2], f[3]); w.z = pk2(f[4], f[5]); w.w = pk2(f[6], f[7]); return w; }
; __device__ __forceinline__ float geluf_(float x) { const float z = x * __builtin_fmaf(x * x, 0.1029432397f, 2.302208198f); const float r = __builtin_amdgcn_rcpf(1.f + __builtin_amdgcn_exp2f(z)); return __builtin_fmaf(-x, r, x); }
; __device__ __forceinline__ void act_fixup(const Params& p, int l, int pm) {
;     ...
;     constexpr int NU = 8 * (DFF / 8), NK = (NU + 511) / 512;
;     u32x4 rg[NK], ru[NK], r1[NK], r2[NK];
; #pragma unroll
;     for (int k = 0; k < NK; ++k) {
;         const int idx = tid + 512 * k;
;         rg[k] = ru[k] = r1[k] = r2[k] = (u32x4){0u, 0u, 0u, 0u};
;         if (idx < NU) {
;             const int rsel = idx / (DFF / 8), c0 = (idx % (DFF / 8)) * 8, blk = pm * 4 + (rsel >> 1), rr = rsel & 1;
;             const bool seq0 = (blk & 31) == 0;
;             rg[k] = *(const u32x4*)(gs01 + ((size_t)blk * 2 + rr) * DFF + c0);
;             ru[k] = *(const u32x4*)(us01 + ((size_t)blk * 2 + rr) * DFF + c0);
;             if (rr == 0) { if (!seq0) { r1[k] = *(const u32x4*)(gs23 + ((size_t)(blk - 1) * 2 + 1) * DFF + c0); r2[k] = *(const u32x4*)(gs23 + ((size_t)(blk - 1) * 2 + 0) * DFF + c0); } }
;             else { r1[k] = *(const u32x4*)(gs01 + ((size_t)blk * 2 + 0) * DFF + c0); if (!seq0) r2[k] = *(const u32x4*)(gs23 + ((size_t)(blk - 1) * 2 + 1) * DFF + c0); }
;         }
;     }
; #pragma unroll
;     for (int k = 0; k < NK; ++k) {
;         const int idx = tid + 512 * k;
;         if (idx < NU) {
;             const int rsel = idx / (DFF / 8), c0 = (idx % (DFF / 8)) * 8, blk = pm * 4 + (rsel >> 1), rr = rsel & 1;
;             float g[8], up[8], g1[8], g2[8], o[8];
;             unpack8(rg[k], g); unpack8(ru[k], up); unpack8(r1[k], g1); unpack8(r2[k], g2);
; #pragma unroll
;             for (int e = 0; e < 8; ++e) o[e] = geluf_(cb[c0 + e] + cw[c0 + e] * g2[e] + cw[DFF + c0 + e] * g1[e] + cw[2 * DFF + c0 + e] * g[e]) * up[e];
;             *(u32x4*)(act + ((size_t)blk * 64 + rr) * DFF + c0) = pack8(o);
.LBB0_65:
	s_waitcnt vmcnt(0)
	v_cmp_gt_u32_e32 vcc, 0x160, v163
	s_and_saveexec_b64 s[0:1], vcc
	s_cbranch_execz .LBB0_56
	v_lshlrev_b32_e32 v2, 4, v163
	v_mov_b32_e32 v3, 0
	v_lshlrev_b32_e32 v6, 5, v163
	v_mov_b32_e32 v7, 0
	v_readlane_b32 s2, v250, 16
	v_readlane_b32 s3, v250, 17
	v_readlane_b32 s36, v250, 18
	v_readlane_b32 s37, v250, 19
	v_readlane_b32 s40, v250, 20
	v_readlane_b32 s41, v250, 21
	v_readlane_b32 s42, v252, 57
	v_readlane_b32 s43, v252, 58
	s_mul_i32 s24, s26, 0xb000
	s_add_u32 s2, s2, s24
	s_addc_u32 s3, s3, 0
	s_add_u32 s36, s36, s24
	s_addc_u32 s37, s37, 0
	s_add_u32 s40, s40, s24
	s_addc_u32 s41, s41, 0
	s_sub_u32 s40, s40, 0x2c00
	s_subb_u32 s41, s41, 0
	s_mul_i32 s24, s26, 0x160000
	s_add_u32 s42, s42, s24
	s_addc_u32 s43, s43, 0
	s_mov_b64 s[44:45], 0x1600
	s_mov_b64 s[46:47], 0x2c00
	s_mov_b64 s[48:49], 0x56a00
	s_and_b32 s24, s26, 7
	v_lshl_add_u64 v[8:9], s[2:3], 0, v[2:3]
	v_lshl_add_u64 v[10:11], s[36:37], 0, v[2:3]
	v_lshl_add_u64 v[12:13], s[40:41], 0, v[2:3]
	v_lshl_add_u64 v[14:15], s[42:43], 0, v[2:3]
	v_lshl_add_u64 v[16:17], s[82:83], 0, v[6:7]
	v_lshl_add_u64 v[18:19], s[80:81], 0, v[6:7]
	global_load_dwordx4 v[20:23], v[16:17], off
	global_load_dwordx4 v[24:27], v[16:17], off offset:16
	global_load_dwordx4 v[28:31], v[18:19], off
	global_load_dwordx4 v[32:35], v[18:19], off offset:16
	v_lshl_add_u64 v[18:19], v[18:19], 0, s[46:47]
	global_load_dwordx4 v[36:39], v[18:19], off
	global_load_dwordx4 v[40:43], v[18:19], off offset:16
	v_lshl_add_u64 v[18:19], v[18:19], 0, s[46:47]
	global_load_dwordx4 v[44:47], v[18:19], off
	global_load_dwordx4 v[48:51], v[18:19], off offset:16
	s_cmp_eq_u32 s24, 0
	s_cbranch_scc1 .Lfx_seq0
	global_load_dwordx4 v[68:71], v[12:13], off
	v_lshl_add_u64 v[4:5], v[12:13], 0, s[44:45]
	global_load_dwordx4 v[72:75], v[4:5], off
	s_branch .Lfx_rows
.Lfx_seq0:
	v_mov_b32_e32 v68, 0
	v_mov_b32_e32 v69, 0
	v_mov_b32_e32 v70, 0
	v_mov_b32_e32 v71, 0
	v_mov_b32_e32 v72, 0
	v_mov_b32_e32 v73, 0
	v_mov_b32_e32 v74, 0
	v_mov_b32_e32 v75, 0
.Lfx_rows:
	global_load_dwordx4 v[52:55], v[8:9], off
	global_load_dwordx4 v[60:63], v[10:11], off
	v_lshl_add_u64 v[8:9], v[8:9], 0, s[44:45]
	v_lshl_add_u64 v[10:11], v[10:11], 0, s[44:45]
	global_load_dwordx4 v[56:59], v[8:9], off
	global_load_dwordx4 v[64:67], v[10:11], off
	v_lshl_add_u64 v[8:9], v[8:9], 0, s[44:45]
	v_lshl_add_u64 v[10:11], v[10:11], 0, s[44:45]
	global_load_dwordx4 v[76:79], v[8:9], off
	global_load_dwordx4 v[84:87], v[10:11], off
	v_lshl_add_u64 v[8:9], v[8:9], 0, s[44:45]
	v_lshl_add_u64 v[10:11], v[10:11], 0, s[44:45]
	global_load_dwordx4 v[80:83], v[8:9], off
	global_load_dwordx4 v[88:91], v[10:11], off
	v_lshl_add_u64 v[8:9], v[8:9], 0, s[44:45]
	v_lshl_add_u64 v[10:11], v[10:11], 0, s[44:45]
	v_lshl_add_u64 v[12:13], v[12:13], 0, s[46:47]
	global_load_dwordx4 v[92:95], v[12:13], off
	v_lshl_add_u64 v[4:5], v[12:13], 0, s[44:45]
	global_load_dwordx4 v[96:99], v[4:5], off
	global_load_dwordx4 v[100:103], v[8:9], off
	global_load_dwordx4 v[108:111], v[10:11], off
	v_lshl_add_u64 v[8:9], v[8:9], 0, s[44:45]
	v_lshl_add_u64 v[10:11], v[10:11], 0, s[44:45]
	global_load_dwordx4 v[104:107], v[8:9], off
	global_load_dwordx4 v[112:115], v[10:11], off
	v_lshl_add_u64 v[8:9], v[8:9], 0, s[44:45]
	v_lshl_add_u64 v[10:11], v[10:11], 0, s[44:45]
	v_lshl_add_u64 v[12:13], v[12:13], 0, s[46:47]
	global_load_dwordx4 v[116:119], v[12:13], off
	v_lshl_add_u64 v[4:5], v[12:13], 0, s[44:45]
	global_load_dwordx4 v[120:123], v[4:5], off
	global_load_dwordx4 v[124:127], v[8:9], off
	global_load_dwordx4 v[132:135], v[10:11], off
	v_lshl_add_u64 v[8:9], v[8:9], 0, s[44:45]
	v_lshl_add_u64 v[10:11], v[10:11], 0, s[44:45]
	global_load_dwordx4 v[128:131], v[8:9], off
	global_load_dwordx4 v[136:139], v[10:11], off
	v_lshl_add_u64 v[12:13], v[12:13], 0, s[46:47]
	global_load_dwordx4 v[140:143], v[12:13], off
	v_lshl_add_u64 v[4:5], v[12:13], 0, s[44:45]
	global_load_dwordx4 v[144:147], v[4:5], off
	s_waitcnt vmcnt(0)
	v_lshlrev_b32_e32 v148, 16, v68
	v_fma_f32 v148, v28, v148, v20
	v_lshlrev_b32_e32 v149, 16, v72
	v_mul_f32_e32 v149, v36, v149
	v_add_f32_e32 v148, v148, v149
	v_lshlrev_b32_e32 v149, 16, v52
	v_mul_f32_e32 v149, v44, v149
	v_add_f32_e32 v148, v148, v149
	v_mul_f32_e32 v149, v148, v148
	v_fmamk_f32 v149, v149, 0x3dd2d3e8, v224
	v_mul_f32_e32 v149, v148, v149
	v_exp_f32_e32 v149, v149
	s_nop 0
	v_add_f32_e32 v149, 1.0, v149
	v_rcp_f32_e32 v149, v149
	s_nop 0
	v_fma_f32 v148, -v148, v149, v148
	v_lshlrev_b32_e32 v149, 16, v60
	v_mul_f32_e32 v156, v148, v149
	v_and_b32_e32 v148, 0xffff0000, v68
	v_fma_f32 v148, v29, v148, v21
	v_and_b32_e32 v149, 0xffff0000, v72
	v_mul_f32_e32 v149, v37, v149
	v_add_f32_e32 v148, v148, v149
	v_and_b32_e32 v149, 0xffff0000, v52
	v_mul_f32_e32 v149, v45, v149
	v_add_f32_e32 v148, v148, v149
	v_mul_f32_e32 v149, v148, v148
	v_fmamk_f32 v149, v149, 0x3dd2d3e8, v224
	v_mul_f32_e32 v149, v148, v149
	v_exp_f32_e32 v149, v149
	s_nop 0
	v_add_f32_e32 v149, 1.0, v149
	v_rcp_f32_e32 v149, v149
	s_nop 0
	v_fma_f32 v148, -v148, v149, v148
	v_and_b32_e32 v149, 0xffff0000, v60
	v_mul_f32_e32 v148, v148, v149
	v_cvt_pk_bf16_f32 v152, v156, v148
	v_lshlrev_b32_e32 v148, 16, v69
	v_fma_f32 v148, v30, v148, v22
	v_lshlrev_b32_e32 v149, 16, v73
	v_mul_f32_e32 v149, v38, v149
	v_add_f32_e32 v148, v148, v149
	v_lshlrev_b32_e32 v149, 16, v53
	v_mul_f32_e32 v149, v46, v149
	v_add_f32_e32 v148, v148, v149
	v_mul_f32_e32 v149, v148, v148
	v_fmamk_f32 v149, v149, 0x3dd2d3e8, v224
	v_mul_f32_e32 v149, v148, v149
	v_exp_f32_e32 v149, v149
	s_nop 0
	v_add_f32_e32 v149, 1.0, v149
	v_rcp_f32_e32 v149, v149
	s_nop 0
; __device__ __forceinline__ u32x4 pack8(const float* f) { u32x4 w; w.x = pk2(f[0], f[1]); w.y = pk2(f[2], f[3]); w.z = pk2(f[4], f[5]); w.w = pk2(f[6], f[7]); return w; }
; __device__ __forceinline__ float geluf_(float x) { const float z = x * __builtin_fmaf(x * x, 0.1029432397f, 2.302208198f); const float r = __builtin_amdgcn_rcpf(1.f + __builtin_amdgcn_exp2f(z)); return __builtin_fmaf(-x, r, x); }
; __device__ __forceinline__ void act_fixup(const Params& p, int l, int pm) {
;     ...
;             float g[8], up[8], g1[8], g2[8], o[8];
;             unpack8(rg[k], g); unpack8(ru[k], up); unpack8(r1[k], g1); unpack8(r2[k], g2);
; #pragma unroll
;             for (int e = 0; e < 8; ++e) o[e] = geluf_(cb[c0 + e] + cw[c0 + e] * g2[e] + cw[DFF + c0 + e] * g1[e] + cw[2 * DFF + c0 + e] * g[e]) * up[e];
;             *(u32x4*)(act + ((size_t)blk * 64 + rr) * DFF + c0) = pack8(o);
	v_fma_f32 v148, -v148, v149, v148
	v_lshlrev_b32_e32 v149, 16, v61
	v_mul_f32_e32 v156, v148, v149
	v_and_b32_e32 v148, 0xffff0000, v69
	v_fma_f32 v148, v31, v148, v23
	v_and_b32_e32 v149, 0xffff0000, v73
	v_mul_f32_e32 v149, v39, v149
	v_add_f32_e32 v148, v148, v149
	v_and_b32_e32 v149, 0xffff0000, v53
	v_mul_f32_e32 v149, v47, v149
	v_add_f32_e32 v148, v148, v149
	v_mul_f32_e32 v149, v148, v148
	v_fmamk_f32 v149, v149, 0x3dd2d3e8, v224
	v_mul_f32_e32 v149, v148, v149
	v_exp_f32_e32 v149, v149
	s_nop 0
	v_add_f32_e32 v149, 1.0, v149
	v_rcp_f32_e32 v149, v149
	s_nop 0
	v_fma_f32 v148, -v148, v149, v148
	v_and_b32_e32 v149, 0xffff0000, v61
	v_mul_f32_e32 v148, v148, v149
	v_cvt_pk_bf16_f32 v153, v156, v148
	v_lshlrev_b32_e32 v148, 16, v70
	v_fma_f32 v148, v32, v148, v24
	v_lshlrev_b32_e32 v149, 16, v74
	v_mul_f32_e32 v149, v40, v149
	v_add_f32_e32 v148, v148, v149
	v_lshlrev_b32_e32 v149, 16, v54
	v_mul_f32_e32 v149, v48, v149
	v_add_f32_e32 v148, v148, v149
	v_mul_f32_e32 v149, v148, v148
	v_fmamk_f32 v149, v149, 0x3dd2d3e8, v224
	v_mul_f32_e32 v149, v148, v149
	v_exp_f32_e32 v149, v149
	s_nop 0
	v_add_f32_e32 v149, 1.0, v149
	v_rcp_f32_e32 v149, v149
	s_nop 0
	v_fma_f32 v148, -v148, v149, v148
	v_lshlrev_b32_e32 v149, 16, v62
	v_mul_f32_e32 v156, v148, v149
	v_and_b32_e32 v148, 0xffff0000, v70
	v_fma_f32 v148, v33, v148, v25
	v_and_b32_e32 v149, 0xffff0000, v74
	v_mul_f32_e32 v149, v41, v149
	v_add_f32_e32 v148, v148, v149
	v_and_b32_e32 v149, 0xffff0000, v54
	v_mul_f32_e32 v149, v49, v149
	v_add_f32_e32 v148, v148, v149
	v_mul_f32_e32 v149, v148, v148
	v_fmamk_f32 v149, v149, 0x3dd2d3e8, v224
	v_mul_f32_e32 v149, v148, v149
	v_exp_f32_e32 v149, v149
	s_nop 0
	v_add_f32_e32 v149, 1.0, v149
	v_rcp_f32_e32 v149, v149
	s_nop 0
	v_fma_f32 v148, -v148, v149, v148
	v_and_b32_e32 v149, 0xffff0000, v62
	v_mul_f32_e32 v148, v148, v149
	v_cvt_pk_bf16_f32 v154, v156, v148
	v_lshlrev_b32_e32 v148, 16, v71
	v_fma_f32 v148, v34, v148, v26
	v_lshlrev_b32_e32 v149, 16, v75
	v_mul_f32_e32 v149, v42, v149
	v_add_f32_e32 v148, v148, v149
	v_lshlrev_b32_e32 v149, 16, v55
	v_mul_f32_e32 v149, v50, v149
	v_add_f32_e32 v148, v148, v149
	v_mul_f32_e32 v149, v148, v148
	v_fmamk_f32 v149, v149, 0x3dd2d3e8, v224
	v_mul_f32_e32 v149, v148, v149
	v_exp_f32_e32 v149, v149
	s_nop 0
	v_add_f32_e32 v149, 1.0, v149
	v_rcp_f32_e32 v149, v149
	s_nop 0
	v_fma_f32 v148, -v148, v149, v148
	v_lshlrev_b32_e32 v149, 16, v63
	v_mul_f32_e32 v156, v148, v149
	v_and_b32_e32 v148, 0xffff0000, v71
	v_fma_f32 v148, v35, v148, v27
	v_and_b32_e32 v149, 0xffff0000, v75
	v_mul_f32_e32 v149, v43, v149
	v_add_f32_e32 v148, v148, v149
	v_and_b32_e32 v149, 0xffff0000, v55
	v_mul_f32_e32 v149, v51, v149
	v_add_f32_e32 v148, v148, v149
	v_mul_f32_e32 v149, v148, v148
	v_fmamk_f32 v149, v149, 0x3dd2d3e8, v224
	v_mul_f32_e32 v149, v148, v149
	v_exp_f32_e32 v149, v149
	s_nop 0
	v_add_f32_e32 v149, 1.0, v149
	v_rcp_f32_e32 v149, v149
	s_nop 0
	v_fma_f32 v148, -v148, v149, v148
	v_and_b32_e32 v149, 0xffff0000, v63
	v_mul_f32_e32 v148, v148, v149
	v_cvt_pk_bf16_f32 v155, v156, v148
	global_store_dwordx4 v[14:15], v[152:155], off
	v_lshl_add_u64 v[14:15], v[14:15], 0, s[44:45]
	s_nop 0
	v_lshlrev_b32_e32 v148, 16, v72
	v_fma_f32 v148, v28, v148, v20
	v_lshlrev_b32_e32 v149, 16, v52
	v_mul_f32_e32 v149, v36, v149
	v_add_f32_e32 v148, v148, v149
	v_lshlrev_b32_e32 v149, 16, v56
	v_mul_f32_e32 v149, v44, v149
	v_add_f32_e32 v148, v148, v149
	v_mul_f32_e32 v149, v148, v148
	v_fmamk_f32 v149, v149, 0x3dd2d3e8, v224
	v_mul_f32_e32 v149, v148, v149
	v_exp_f32_e32 v149, v149
	s_nop 0
	v_add_f32_e32 v149, 1.0, v149
	v_rcp_f32_e32 v149, v149
	s_nop 0
	v_fma_f32 v148, -v148, v149, v148
	v_lshlrev_b32_e32 v149, 16, v64
	v_mul_f32_e32 v156, v148, v149
	v_and_b32_e32 v148, 0xffff0000, v72
	v_fma_f32 v148, v29, v148, v21
	v_and_b32_e32 v149, 0xffff0000, v52
	v_mul_f32_e32 v149, v37, v149
	v_add_f32_e32 v148, v148, v149
	v_and_b32_e32 v149, 0xffff0000, v56
	v_mul_f32_e32 v149, v45, v149
	v_add_f32_e32 v148, v148, v149
	v_mul_f32_e32 v149, v148, v148
	v_fmamk_f32 v149, v149, 0x3dd2d3e8, v224
	v_mul_f32_e32 v149, v148, v149
	v_exp_f32_e32 v149, v149
	s_nop 0
	v_add_f32_e32 v149, 1.0, v149
	v_rcp_f32_e32 v149, v149
	s_nop 0
	v_fma_f32 v148, -v148, v149, v148
	v_and_b32_e32 v149, 0xffff0000, v64
	v_mul_f32_e32 v148, v148, v149
	v_cvt_pk_bf16_f32 v152, v156, v148
	v_lshlrev_b32_e32 v148, 16, v73
	v_fma_f32 v148, v30, v148, v22
	v_lshlrev_b32_e32 v149, 16, v53
	v_mul_f32_e32 v149, v38, v149
	v_add_f32_e32 v148, v148, v149
	v_lshlrev_b32_e32 v149, 16, v57
	v_mul_f32_e32 v149, v46, v149
	v_add_f32_e32 v148, v148, v149
	v_mul_f32_e32 v149, v148, v148
	v_fmamk_f32 v149, v149, 0x3dd2d3e8, v224
	v_mul_f32_e32 v149, v148, v149
	v_exp_f32_e32 v149, v149
	s_nop 0
	v_add_f32_e32 v149, 1.0, v149
	v_rcp_f32_e32 v149, v149
	s_nop 0
	v_fma_f32 v148, -v148, v149, v148
	v_lshlrev_b32_e32 v149, 16, v65
	v_mul_f32_e32 v156, v148, v149
	v_and_b32_e32 v148, 0xffff0000, v73
	v_fma_f32 v148, v31, v148, v23
	v_and_b32_e32 v149, 0xffff0000, v53
	v_mul_f32_e32 v149, v39, v149
	v_add_f32_e32 v148, v148, v149
	v_and_b32_e32 v149, 0xffff0000, v57
	v_mul_f32_e32 v149, v47, v149
	v_add_f32_e32 v148, v148, v149
	v_mul_f32_e32 v149, v148, v148
	v_fmamk_f32 v149, v149, 0x3dd2d3e8, v224
	v_mul_f32_e32 v149, v148, v149
	v_exp_f32_e32 v149, v149
	s_nop 0
	v_add_f32_e32 v149, 1.0, v149
	v_rcp_f32_e32 v149, v149
	s_nop 0
	v_fma_f32 v148, -v148, v149, v148
	v_and_b32_e32 v149, 0xffff0000, v65
	v_mul_f32_e32 v148, v148, v149
	v_cvt_pk_bf16_f32 v153, v156, v148
	v_lshlrev_b32_e32 v148, 16, v74
	v_fma_f32 v148, v32, v148, v24
	v_lshlrev_b32_e32 v149, 16, v54
; __device__ __forceinline__ u32x4 pack8(const float* f) { u32x4 w; w.x = pk2(f[0], f[1]); w.y = pk2(f[2], f[3]); w.z = pk2(f[4], f[5]); w.w = pk2(f[6], f[7]); return w; }
; __device__ __forceinline__ float geluf_(float x) { const float z = x * __builtin_fmaf(x * x, 0.1029432397f, 2.302208198f); const float r = __builtin_amdgcn_rcpf(1.f + __builtin_amdgcn_exp2f(z)); return __builtin_fmaf(-x, r, x); }
; __device__ __forceinline__ void act_fixup(const Params& p, int l, int pm) {
;     ...
;             float g[8], up[8], g1[8], g2[8], o[8];
;             unpack8(rg[k], g); unpack8(ru[k], up); unpack8(r1[k], g1); unpack8(r2[k], g2);
; #pragma unroll
;             for (int e = 0; e < 8; ++e) o[e] = geluf_(cb[c0 + e] + cw[c0 + e] * g2[e] + cw[DFF + c0 + e] * g1[e] + cw[2 * DFF + c0 + e] * g[e]) * up[e];
;             *(u32x4*)(act + ((size_t)blk * 64 + rr) * DFF + c0) = pack8(o);
	v_mul_f32_e32 v149, v40, v149
	v_add_f32_e32 v148, v148, v149
	v_lshlrev_b32_e32 v149, 16, v58
	v_mul_f32_e32 v149, v48, v149
	v_add_f32_e32 v148, v148, v149
	v_mul_f32_e32 v149, v148, v148
	v_fmamk_f32 v149, v149, 0x3dd2d3e8, v224
	v_mul_f32_e32 v149, v148, v149
	v_exp_f32_e32 v149, v149
	s_nop 0
	v_add_f32_e32 v149, 1.0, v149
	v_rcp_f32_e32 v149, v149
	s_nop 0
	v_fma_f32 v148, -v148, v149, v148
	v_lshlrev_b32_e32 v149, 16, v66
	v_mul_f32_e32 v156, v148, v149
	v_and_b32_e32 v148, 0xffff0000, v74
	v_fma_f32 v148, v33, v148, v25
	v_and_b32_e32 v149, 0xffff0000, v54
	v_mul_f32_e32 v149, v41, v149
	v_add_f32_e32 v148, v148, v149
	v_and_b32_e32 v149, 0xffff0000, v58
	v_mul_f32_e32 v149, v49, v149
	v_add_f32_e32 v148, v148, v149
	v_mul_f32_e32 v149, v148, v148
	v_fmamk_f32 v149, v149, 0x3dd2d3e8, v224
	v_mul_f32_e32 v149, v148, v149
	v_exp_f32_e32 v149, v149
	s_nop 0
	v_add_f32_e32 v149, 1.0, v149
	v_rcp_f32_e32 v149, v149
	s_nop 0
	v_fma_f32 v148, -v148, v149, v148
	v_and_b32_e32 v149, 0xffff0000, v66
	v_mul_f32_e32 v148, v148, v149
	v_cvt_pk_bf16_f32 v154, v156, v148
	v_lshlrev_b32_e32 v148, 16, v75
	v_fma_f32 v148, v34, v148, v26
	v_lshlrev_b32_e32 v149, 16, v55
	v_mul_f32_e32 v149, v42, v149
	v_add_f32_e32 v148, v148, v149
	v_lshlrev_b32_e32 v149, 16, v59
	v_mul_f32_e32 v149, v50, v149
	v_add_f32_e32 v148, v148, v149
	v_mul_f32_e32 v149, v148, v148
	v_fmamk_f32 v149, v149, 0x3dd2d3e8, v224
	v_mul_f32_e32 v149, v148, v149
	v_exp_f32_e32 v149, v149
	s_nop 0
	v_add_f32_e32 v149, 1.0, v149
	v_rcp_f32_e32 v149, v149
	s_nop 0
	v_fma_f32 v148, -v148, v149, v148
	v_lshlrev_b32_e32 v149, 16, v67
	v_mul_f32_e32 v156, v148, v149
	v_and_b32_e32 v148, 0xffff0000, v75
	v_fma_f32 v148, v35, v148, v27
	v_and_b32_e32 v149, 0xffff0000, v55
	v_mul_f32_e32 v149, v43, v149
	v_add_f32_e32 v148, v148, v149
	v_and_b32_e32 v149, 0xffff0000, v59
	v_mul_f32_e32 v149, v51, v149
	v_add_f32_e32 v148, v148, v149
	v_mul_f32_e32 v149, v148, v148
	v_fmamk_f32 v149, v149, 0x3dd2d3e8, v224
	v_mul_f32_e32 v149, v148, v149
	v_exp_f32_e32 v149, v149
	s_nop 0
	v_add_f32_e32 v149, 1.0, v149
	v_rcp_f32_e32 v149, v149
	s_nop 0
	v_fma_f32 v148, -v148, v149, v148
	v_and_b32_e32 v149, 0xffff0000, v67
	v_mul_f32_e32 v148, v148, v149
	v_cvt_pk_bf16_f32 v155, v156, v148
	global_store_dwordx4 v[14:15], v[152:155], off
	v_lshl_add_u64 v[14:15], v[14:15], 0, s[48:49]
	s_nop 0
	v_lshlrev_b32_e32 v148, 16, v92
	v_fma_f32 v148, v28, v148, v20
	v_lshlrev_b32_e32 v149, 16, v96
	v_mul_f32_e32 v149, v36, v149
	v_add_f32_e32 v148, v148, v149
	v_lshlrev_b32_e32 v149, 16, v76
	v_mul_f32_e32 v149, v44, v149
	v_add_f32_e32 v148, v148, v149
	v_mul_f32_e32 v149, v148, v148
	v_fmamk_f32 v149, v149, 0x3dd2d3e8, v224
	v_mul_f32_e32 v149, v148, v149
	v_exp_f32_e32 v149, v149
	s_nop 0
	v_add_f32_e32 v149, 1.0, v149
	v_rcp_f32_e32 v149, v149
	s_nop 0
	v_fma_f32 v148, -v148, v149, v148
	v_lshlrev_b32_e32 v149, 16, v84
	v_mul_f32_e32 v156, v148, v149
	v_and_b32_e32 v148, 0xffff0000, v92
	v_fma_f32 v148, v29, v148, v21
	v_and_b32_e32 v149, 0xffff0000, v96
	v_mul_f32_e32 v149, v37, v149
	v_add_f32_e32 v148, v148, v149
	v_and_b32_e32 v149, 0xffff0000, v76
	v_mul_f32_e32 v149, v45, v149
	v_add_f32_e32 v148, v148, v149
	v_mul_f32_e32 v149, v148, v148
	v_fmamk_f32 v149, v149, 0x3dd2d3e8, v224
	v_mul_f32_e32 v149, v148, v149
	v_exp_f32_e32 v149, v149
	s_nop 0
	v_add_f32_e32 v149, 1.0, v149
	v_rcp_f32_e32 v149, v149
	s_nop 0
	v_fma_f32 v148, -v148, v149, v148
	v_and_b32_e32 v149, 0xffff0000, v84
	v_mul_f32_e32 v148, v148, v149
	v_cvt_pk_bf16_f32 v152, v156, v148
	v_lshlrev_b32_e32 v148, 16, v93
	v_fma_f32 v148, v30, v148, v22
	v_lshlrev_b32_e32 v149, 16, v97
	v_mul_f32_e32 v149, v38, v149
	v_add_f32_e32 v148, v148, v149
	v_lshlrev_b32_e32 v149, 16, v77
	v_mul_f32_e32 v149, v46, v149
	v_add_f32_e32 v148, v148, v149
	v_mul_f32_e32 v149, v148, v148
	v_fmamk_f32 v149, v149, 0x3dd2d3e8, v224
	v_mul_f32_e32 v149, v148, v149
	v_exp_f32_e32 v149, v149
	s_nop 0
	v_add_f32_e32 v149, 1.0, v149
	v_rcp_f32_e32 v149, v149
	s_nop 0
	v_fma_f32 v148, -v148, v149, v148
	v_lshlrev_b32_e32 v149, 16, v85
	v_mul_f32_e32 v156, v148, v149
	v_and_b32_e32 v148, 0xffff0000, v93
	v_fma_f32 v148, v31, v148, v23
	v_and_b32_e32 v149, 0xffff0000, v97
	v_mul_f32_e32 v149, v39, v149
	v_add_f32_e32 v148, v148, v149
	v_and_b32_e32 v149, 0xffff0000, v77
	v_mul_f32_e32 v149, v47, v149
	v_add_f32_e32 v148, v148, v149
	v_mul_f32_e32 v149, v148, v148
	v_fmamk_f32 v149, v149, 0x3dd2d3e8, v224
	v_mul_f32_e32 v149, v148, v149
	v_exp_f32_e32 v149, v149
	s_nop 0
	v_add_f32_e32 v149, 1.0, v149
	v_rcp_f32_e32 v149, v149
	s_nop 0
	v_fma_f32 v148, -v148, v149, v148
	v_and_b32_e32 v149, 0xffff0000, v85
	v_mul_f32_e32 v148, v148, v149
	v_cvt_pk_bf16_f32 v153, v156, v148
	v_lshlrev_b32_e32 v148, 16, v94
	v_fma_f32 v148, v32, v148, v24
	v_lshlrev_b32_e32 v149, 16, v98
	v_mul_f32_e32 v149, v40, v149
	v_add_f32_e32 v148, v148, v149
	v_lshlrev_b32_e32 v149, 16, v78
	v_mul_f32_e32 v149, v48, v149
	v_add_f32_e32 v148, v148, v149
	v_mul_f32_e32 v149, v148, v148
	v_fmamk_f32 v149, v149, 0x3dd2d3e8, v224
	v_mul_f32_e32 v149, v148, v149
	v_exp_f32_e32 v149, v149
	s_nop 0
	v_add_f32_e32 v149, 1.0, v149
	v_rcp_f32_e32 v149, v149
	s_nop 0
	v_fma_f32 v148, -v148, v149, v148
	v_lshlrev_b32_e32 v149, 16, v86
	v_mul_f32_e32 v156, v148, v149
	v_and_b32_e32 v148, 0xffff0000, v94
	v_fma_f32 v148, v33, v148, v25
	v_and_b32_e32 v149, 0xffff0000, v98
	v_mul_f32_e32 v149, v41, v149
	v_add_f32_e32 v148, v148, v149
	v_and_b32_e32 v149, 0xffff0000, v78
	v_mul_f32_e32 v149, v49, v149
	v_add_f32_e32 v148, v148, v149
	v_mul_f32_e32 v149, v148, v148
	v_fmamk_f32 v149, v149, 0x3dd2d3e8, v224
; __device__ __forceinline__ u32x4 pack8(const float* f) { u32x4 w; w.x = pk2(f[0], f[1]); w.y = pk2(f[2], f[3]); w.z = pk2(f[4], f[5]); w.w = pk2(f[6], f[7]); return w; }
; __device__ __forceinline__ float geluf_(float x) { const float z = x * __builtin_fmaf(x * x, 0.1029432397f, 2.302208198f); const float r = __builtin_amdgcn_rcpf(1.f + __builtin_amdgcn_exp2f(z)); return __builtin_fmaf(-x, r, x); }
; __device__ __forceinline__ void act_fixup(const Params& p, int l, int pm) {
;     ...
;             float g[8], up[8], g1[8], g2[8], o[8];
;             unpack8(rg[k], g); unpack8(ru[k], up); unpack8(r1[k], g1); unpack8(r2[k], g2);
; #pragma unroll
;             for (int e = 0; e < 8; ++e) o[e] = geluf_(cb[c0 + e] + cw[c0 + e] * g2[e] + cw[DFF + c0 + e] * g1[e] + cw[2 * DFF + c0 + e] * g[e]) * up[e];
;             *(u32x4*)(act + ((size_t)blk * 64 + rr) * DFF + c0) = pack8(o);
	v_mul_f32_e32 v149, v148, v149
	v_exp_f32_e32 v149, v149
	s_nop 0
	v_add_f32_e32 v149, 1.0, v149
	v_rcp_f32_e32 v149, v149
	s_nop 0
	v_fma_f32 v148, -v148, v149, v148
	v_and_b32_e32 v149, 0xffff0000, v86
	v_mul_f32_e32 v148, v148, v149
	v_cvt_pk_bf16_f32 v154, v156, v148
	v_lshlrev_b32_e32 v148, 16, v95
	v_fma_f32 v148, v34, v148, v26
	v_lshlrev_b32_e32 v149, 16, v99
	v_mul_f32_e32 v149, v42, v149
	v_add_f32_e32 v148, v148, v149
	v_lshlrev_b32_e32 v149, 16, v79
	v_mul_f32_e32 v149, v50, v149
	v_add_f32_e32 v148, v148, v149
	v_mul_f32_e32 v149, v148, v148
	v_fmamk_f32 v149, v149, 0x3dd2d3e8, v224
	v_mul_f32_e32 v149, v148, v149
	v_exp_f32_e32 v149, v149
	s_nop 0
	v_add_f32_e32 v149, 1.0, v149
	v_rcp_f32_e32 v149, v149
	s_nop 0
	v_fma_f32 v148, -v148, v149, v148
	v_lshlrev_b32_e32 v149, 16, v87
	v_mul_f32_e32 v156, v148, v149
	v_and_b32_e32 v148, 0xffff0000, v95
	v_fma_f32 v148, v35, v148, v27
	v_and_b32_e32 v149, 0xffff0000, v99
	v_mul_f32_e32 v149, v43, v149
	v_add_f32_e32 v148, v148, v149
	v_and_b32_e32 v149, 0xffff0000, v79
	v_mul_f32_e32 v149, v51, v149
	v_add_f32_e32 v148, v148, v149
	v_mul_f32_e32 v149, v148, v148
	v_fmamk_f32 v149, v149, 0x3dd2d3e8, v224
	v_mul_f32_e32 v149, v148, v149
	v_exp_f32_e32 v149, v149
	s_nop 0
	v_add_f32_e32 v149, 1.0, v149
	v_rcp_f32_e32 v149, v149
	s_nop 0
	v_fma_f32 v148, -v148, v149, v148
	v_and_b32_e32 v149, 0xffff0000, v87
	v_mul_f32_e32 v148, v148, v149
	v_cvt_pk_bf16_f32 v155, v156, v148
	global_store_dwordx4 v[14:15], v[152:155], off
	v_lshl_add_u64 v[14:15], v[14:15], 0, s[44:45]
	s_nop 0
	v_lshlrev_b32_e32 v148, 16, v96
	v_fma_f32 v148, v28, v148, v20
	v_lshlrev_b32_e32 v149, 16, v76
	v_mul_f32_e32 v149, v36, v149
	v_add_f32_e32 v148, v148, v149
	v_lshlrev_b32_e32 v149, 16, v80
	v_mul_f32_e32 v149, v44, v149
	v_add_f32_e32 v148, v148, v149
	v_mul_f32_e32 v149, v148, v148
	v_fmamk_f32 v149, v149, 0x3dd2d3e8, v224
	v_mul_f32_e32 v149, v148, v149
	v_exp_f32_e32 v149, v149
	s_nop 0
	v_add_f32_e32 v149, 1.0, v149
	v_rcp_f32_e32 v149, v149
	s_nop 0
	v_fma_f32 v148, -v148, v149, v148
	v_lshlrev_b32_e32 v149, 16, v88
	v_mul_f32_e32 v156, v148, v149
	v_and_b32_e32 v148, 0xffff0000, v96
	v_fma_f32 v148, v29, v148, v21
	v_and_b32_e32 v149, 0xffff0000, v76
	v_mul_f32_e32 v149, v37, v149
	v_add_f32_e32 v148, v148, v149
	v_and_b32_e32 v149, 0xffff0000, v80
	v_mul_f32_e32 v149, v45, v149
	v_add_f32_e32 v148, v148, v149
	v_mul_f32_e32 v149, v148, v148
	v_fmamk_f32 v149, v149, 0x3dd2d3e8, v224
	v_mul_f32_e32 v149, v148, v149
	v_exp_f32_e32 v149, v149
	s_nop 0
	v_add_f32_e32 v149, 1.0, v149
	v_rcp_f32_e32 v149, v149
	s_nop 0
	v_fma_f32 v148, -v148, v149, v148
	v_and_b32_e32 v149, 0xffff0000, v88
	v_mul_f32_e32 v148, v148, v149
	v_cvt_pk_bf16_f32 v152, v156, v148
	v_lshlrev_b32_e32 v148, 16, v97
	v_fma_f32 v148, v30, v148, v22
	v_lshlrev_b32_e32 v149, 16, v77
	v_mul_f32_e32 v149, v38, v149
	v_add_f32_e32 v148, v148, v149
	v_lshlrev_b32_e32 v149, 16, v81
	v_mul_f32_e32 v149, v46, v149
	v_add_f32_e32 v148, v148, v149
	v_mul_f32_e32 v149, v148, v148
	v_fmamk_f32 v149, v149, 0x3dd2d3e8, v224
	v_mul_f32_e32 v149, v148, v149
	v_exp_f32_e32 v149, v149
	s_nop 0
	v_add_f32_e32 v149, 1.0, v149
	v_rcp_f32_e32 v149, v149
	s_nop 0
	v_fma_f32 v148, -v148, v149, v148
	v_lshlrev_b32_e32 v149, 16, v89
	v_mul_f32_e32 v156, v148, v149
	v_and_b32_e32 v148, 0xffff0000, v97
	v_fma_f32 v148, v31, v148, v23
	v_and_b32_e32 v149, 0xffff0000, v77
	v_mul_f32_e32 v149, v39, v149
	v_add_f32_e32 v148, v148, v149
	v_and_b32_e32 v149, 0xffff0000, v81
	v_mul_f32_e32 v149, v47, v149
	v_add_f32_e32 v148, v148, v149
	v_mul_f32_e32 v149, v148, v148
	v_fmamk_f32 v149, v149, 0x3dd2d3e8, v224
	v_mul_f32_e32 v149, v148, v149
	v_exp_f32_e32 v149, v149
	s_nop 0
	v_add_f32_e32 v149, 1.0, v149
	v_rcp_f32_e32 v149, v149
	s_nop 0
	v_fma_f32 v148, -v148, v149, v148
	v_and_b32_e32 v149, 0xffff0000, v89
	v_mul_f32_e32 v148, v148, v149
	v_cvt_pk_bf16_f32 v153, v156, v148
	v_lshlrev_b32_e32 v148, 16, v98
	v_fma_f32 v148, v32, v148, v24
	v_lshlrev_b32_e32 v149, 16, v78
	v_mul_f32_e32 v149, v40, v149
	v_add_f32_e32 v148, v148, v149
	v_lshlrev_b32_e32 v149, 16, v82
	v_mul_f32_e32 v149, v48, v149
	v_add_f32_e32 v148, v148, v149
	v_mul_f32_e32 v149, v148, v148
	v_fmamk_f32 v149, v149, 0x3dd2d3e8, v224
	v_mul_f32_e32 v149, v148, v149
	v_exp_f32_e32 v149, v149
	s_nop 0
	v_add_f32_e32 v149, 1.0, v149
	v_rcp_f32_e32 v149, v149
	s_nop 0
	v_fma_f32 v148, -v148, v149, v148
	v_lshlrev_b32_e32 v149, 16, v90
	v_mul_f32_e32 v156, v148, v149
	v_and_b32_e32 v148, 0xffff0000, v98
	v_fma_f32 v148, v33, v148, v25
	v_and_b32_e32 v149, 0xffff0000, v78
	v_mul_f32_e32 v149, v41, v149
	v_add_f32_e32 v148, v148, v149
	v_and_b32_e32 v149, 0xffff0000, v82
	v_mul_f32_e32 v149, v49, v149
	v_add_f32_e32 v148, v148, v149
	v_mul_f32_e32 v149, v148, v148
	v_fmamk_f32 v149, v149, 0x3dd2d3e8, v224
	v_mul_f32_e32 v149, v148, v149
	v_exp_f32_e32 v149, v149
	s_nop 0
	v_add_f32_e32 v149, 1.0, v149
	v_rcp_f32_e32 v149, v149
	s_nop 0
	v_fma_f32 v148, -v148, v149, v148
	v_and_b32_e32 v149, 0xffff0000, v90
	v_mul_f32_e32 v148, v148, v149
	v_cvt_pk_bf16_f32 v154, v156, v148
	v_lshlrev_b32_e32 v148, 16, v99
	v_fma_f32 v148, v34, v148, v26
	v_lshlrev_b32_e32 v149, 16, v79
	v_mul_f32_e32 v149, v42, v149
	v_add_f32_e32 v148, v148, v149
	v_lshlrev_b32_e32 v149, 16, v83
	v_mul_f32_e32 v149, v50, v149
	v_add_f32_e32 v148, v148, v149
	v_mul_f32_e32 v149, v148, v148
	v_fmamk_f32 v149, v149, 0x3dd2d3e8, v224
	v_mul_f32_e32 v149, v148, v149
	v_exp_f32_e32 v149, v149
	s_nop 0
	v_add_f32_e32 v149, 1.0, v149
	v_rcp_f32_e32 v149, v149
	s_nop 0
	v_fma_f32 v148, -v148, v149, v148
	v_lshlrev_b32_e32 v149, 16, v91
; __device__ __forceinline__ u32x4 pack8(const float* f) { u32x4 w; w.x = pk2(f[0], f[1]); w.y = pk2(f[2], f[3]); w.z = pk2(f[4], f[5]); w.w = pk2(f[6], f[7]); return w; }
; __device__ __forceinline__ float geluf_(float x) { const float z = x * __builtin_fmaf(x * x, 0.1029432397f, 2.302208198f); const float r = __builtin_amdgcn_rcpf(1.f + __builtin_amdgcn_exp2f(z)); return __builtin_fmaf(-x, r, x); }
; __device__ __forceinline__ void act_fixup(const Params& p, int l, int pm) {
;     ...
;             float g[8], up[8], g1[8], g2[8], o[8];
;             unpack8(rg[k], g); unpack8(ru[k], up); unpack8(r1[k], g1); unpack8(r2[k], g2);
; #pragma unroll
;             for (int e = 0; e < 8; ++e) o[e] = geluf_(cb[c0 + e] + cw[c0 + e] * g2[e] + cw[DFF + c0 + e] * g1[e] + cw[2 * DFF + c0 + e] * g[e]) * up[e];
;             *(u32x4*)(act + ((size_t)blk * 64 + rr) * DFF + c0) = pack8(o);
	v_mul_f32_e32 v156, v148, v149
	v_and_b32_e32 v148, 0xffff0000, v99
	v_fma_f32 v148, v35, v148, v27
	v_and_b32_e32 v149, 0xffff0000, v79
	v_mul_f32_e32 v149, v43, v149
	v_add_f32_e32 v148, v148, v149
	v_and_b32_e32 v149, 0xffff0000, v83
	v_mul_f32_e32 v149, v51, v149
	v_add_f32_e32 v148, v148, v149
	v_mul_f32_e32 v149, v148, v148
	v_fmamk_f32 v149, v149, 0x3dd2d3e8, v224
	v_mul_f32_e32 v149, v148, v149
	v_exp_f32_e32 v149, v149
	s_nop 0
	v_add_f32_e32 v149, 1.0, v149
	v_rcp_f32_e32 v149, v149
	s_nop 0
	v_fma_f32 v148, -v148, v149, v148
	v_and_b32_e32 v149, 0xffff0000, v91
	v_mul_f32_e32 v148, v148, v149
	v_cvt_pk_bf16_f32 v155, v156, v148
	global_store_dwordx4 v[14:15], v[152:155], off
	v_lshl_add_u64 v[14:15], v[14:15], 0, s[48:49]
	s_nop 0
	v_lshlrev_b32_e32 v148, 16, v116
	v_fma_f32 v148, v28, v148, v20
	v_lshlrev_b32_e32 v149, 16, v120
	v_mul_f32_e32 v149, v36, v149
	v_add_f32_e32 v148, v148, v149
	v_lshlrev_b32_e32 v149, 16, v100
	v_mul_f32_e32 v149, v44, v149
	v_add_f32_e32 v148, v148, v149
	v_mul_f32_e32 v149, v148, v148
	v_fmamk_f32 v149, v149, 0x3dd2d3e8, v224
	v_mul_f32_e32 v149, v148, v149
	v_exp_f32_e32 v149, v149
	s_nop 0
	v_add_f32_e32 v149, 1.0, v149
	v_rcp_f32_e32 v149, v149
	s_nop 0
	v_fma_f32 v148, -v148, v149, v148
	v_lshlrev_b32_e32 v149, 16, v108
	v_mul_f32_e32 v156, v148, v149
	v_and_b32_e32 v148, 0xffff0000, v116
	v_fma_f32 v148, v29, v148, v21
	v_and_b32_e32 v149, 0xffff0000, v120
	v_mul_f32_e32 v149, v37, v149
	v_add_f32_e32 v148, v148, v149
	v_and_b32_e32 v149, 0xffff0000, v100
	v_mul_f32_e32 v149, v45, v149
	v_add_f32_e32 v148, v148, v149
	v_mul_f32_e32 v149, v148, v148
	v_fmamk_f32 v149, v149, 0x3dd2d3e8, v224
	v_mul_f32_e32 v149, v148, v149
	v_exp_f32_e32 v149, v149
	s_nop 0
	v_add_f32_e32 v149, 1.0, v149
	v_rcp_f32_e32 v149, v149
	s_nop 0
	v_fma_f32 v148, -v148, v149, v148
	v_and_b32_e32 v149, 0xffff0000, v108
	v_mul_f32_e32 v148, v148, v149
	v_cvt_pk_bf16_f32 v152, v156, v148
	v_lshlrev_b32_e32 v148, 16, v117
	v_fma_f32 v148, v30, v148, v22
	v_lshlrev_b32_e32 v149, 16, v121
	v_mul_f32_e32 v149, v38, v149
	v_add_f32_e32 v148, v148, v149
	v_lshlrev_b32_e32 v149, 16, v101
	v_mul_f32_e32 v149, v46, v149
	v_add_f32_e32 v148, v148, v149
	v_mul_f32_e32 v149, v148, v148
	v_fmamk_f32 v149, v149, 0x3dd2d3e8, v224
	v_mul_f32_e32 v149, v148, v149
	v_exp_f32_e32 v149, v149
	s_nop 0
	v_add_f32_e32 v149, 1.0, v149
	v_rcp_f32_e32 v149, v149
	s_nop 0
	v_fma_f32 v148, -v148, v149, v148
	v_lshlrev_b32_e32 v149, 16, v109
	v_mul_f32_e32 v156, v148, v149
	v_and_b32_e32 v148, 0xffff0000, v117
	v_fma_f32 v148, v31, v148, v23
	v_and_b32_e32 v149, 0xffff0000, v121
	v_mul_f32_e32 v149, v39, v149
	v_add_f32_e32 v148, v148, v149
	v_and_b32_e32 v149, 0xffff0000, v101
	v_mul_f32_e32 v149, v47, v149
	v_add_f32_e32 v148, v148, v149
	v_mul_f32_e32 v149, v148, v148
	v_fmamk_f32 v149, v149, 0x3dd2d3e8, v224
	v_mul_f32_e32 v149, v148, v149
	v_exp_f32_e32 v149, v149
	s_nop 0
	v_add_f32_e32 v149, 1.0, v149
	v_rcp_f32_e32 v149, v149
	s_nop 0
	v_fma_f32 v148, -v148, v149, v148
	v_and_b32_e32 v149, 0xffff0000, v109
	v_mul_f32_e32 v148, v148, v149
	v_cvt_pk_bf16_f32 v153, v156, v148
	v_lshlrev_b32_e32 v148, 16, v118
	v_fma_f32 v148, v32, v148, v24
	v_lshlrev_b32_e32 v149, 16, v122
	v_mul_f32_e32 v149, v40, v149
	v_add_f32_e32 v148, v148, v149
	v_lshlrev_b32_e32 v149, 16, v102
	v_mul_f32_e32 v149, v48, v149
	v_add_f32_e32 v148, v148, v149
	v_mul_f32_e32 v149, v148, v148
	v_fmamk_f32 v149, v149, 0x3dd2d3e8, v224
	v_mul_f32_e32 v149, v148, v149
	v_exp_f32_e32 v149, v149
	s_nop 0
	v_add_f32_e32 v149, 1.0, v149
	v_rcp_f32_e32 v149, v149
	s_nop 0
	v_fma_f32 v148, -v148, v149, v148
	v_lshlrev_b32_e32 v149, 16, v110
	v_mul_f32_e32 v156, v148, v149
	v_and_b32_e32 v148, 0xffff0000, v118
	v_fma_f32 v148, v33, v148, v25
	v_and_b32_e32 v149, 0xffff0000, v122
	v_mul_f32_e32 v149, v41, v149
	v_add_f32_e32 v148, v148, v149
	v_and_b32_e32 v149, 0xffff0000, v102
	v_mul_f32_e32 v149, v49, v149
	v_add_f32_e32 v148, v148, v149
	v_mul_f32_e32 v149, v148, v148
	v_fmamk_f32 v149, v149, 0x3dd2d3e8, v224
	v_mul_f32_e32 v149, v148, v149
	v_exp_f32_e32 v149, v149
	s_nop 0
	v_add_f32_e32 v149, 1.0, v149
	v_rcp_f32_e32 v149, v149
	s_nop 0
	v_fma_f32 v148, -v148, v149, v148
	v_and_b32_e32 v149, 0xffff0000, v110
	v_mul_f32_e32 v148, v148, v149
	v_cvt_pk_bf16_f32 v154, v156, v148
	v_lshlrev_b32_e32 v148, 16, v119
	v_fma_f32 v148, v34, v148, v26
	v_lshlrev_b32_e32 v149, 16, v123
	v_mul_f32_e32 v149, v42, v149
	v_add_f32_e32 v148, v148, v149
	v_lshlrev_b32_e32 v149, 16, v103
	v_mul_f32_e32 v149, v50, v149
	v_add_f32_e32 v148, v148, v149
	v_mul_f32_e32 v149, v148, v148
	v_fmamk_f32 v149, v149, 0x3dd2d3e8, v224
	v_mul_f32_e32 v149, v148, v149
	v_exp_f32_e32 v149, v149
	s_nop 0
	v_add_f32_e32 v149, 1.0, v149
	v_rcp_f32_e32 v149, v149
	s_nop 0
	v_fma_f32 v148, -v148, v149, v148
	v_lshlrev_b32_e32 v149, 16, v111
	v_mul_f32_e32 v156, v148, v149
	v_and_b32_e32 v148, 0xffff0000, v119
	v_fma_f32 v148, v35, v148, v27
	v_and_b32_e32 v149, 0xffff0000, v123
	v_mul_f32_e32 v149, v43, v149
	v_add_f32_e32 v148, v148, v149
	v_and_b32_e32 v149, 0xffff0000, v103
	v_mul_f32_e32 v149, v51, v149
	v_add_f32_e32 v148, v148, v149
	v_mul_f32_e32 v149, v148, v148
	v_fmamk_f32 v149, v149, 0x3dd2d3e8, v224
	v_mul_f32_e32 v149, v148, v149
	v_exp_f32_e32 v149, v149
	s_nop 0
	v_add_f32_e32 v149, 1.0, v149
	v_rcp_f32_e32 v149, v149
	s_nop 0
	v_fma_f32 v148, -v148, v149, v148
	v_and_b32_e32 v149, 0xffff0000, v111
	v_mul_f32_e32 v148, v148, v149
	v_cvt_pk_bf16_f32 v155, v156, v148
	global_store_dwordx4 v[14:15], v[152:155], off
	v_lshl_add_u64 v[14:15], v[14:15], 0, s[44:45]
	s_nop 0
	v_lshlrev_b32_e32 v148, 16, v120
; __device__ __forceinline__ u32x4 pack8(const float* f) { u32x4 w; w.x = pk2(f[0], f[1]); w.y = pk2(f[2], f[3]); w.z = pk2(f[4], f[5]); w.w = pk2(f[6], f[7]); return w; }
; __device__ __forceinline__ float geluf_(float x) { const float z = x * __builtin_fmaf(x * x, 0.1029432397f, 2.302208198f); const float r = __builtin_amdgcn_rcpf(1.f + __builtin_amdgcn_exp2f(z)); return __builtin_fmaf(-x, r, x); }
; __device__ __forceinline__ void act_fixup(const Params& p, int l, int pm) {
;     ...
;             float g[8], up[8], g1[8], g2[8], o[8];
;             unpack8(rg[k], g); unpack8(ru[k], up); unpack8(r1[k], g1); unpack8(r2[k], g2);
; #pragma unroll
;             for (int e = 0; e < 8; ++e) o[e] = geluf_(cb[c0 + e] + cw[c0 + e] * g2[e] + cw[DFF + c0 + e] * g1[e] + cw[2 * DFF + c0 + e] * g[e]) * up[e];
;             *(u32x4*)(act + ((size_t)blk * 64 + rr) * DFF + c0) = pack8(o);
	v_fma_f32 v148, v28, v148, v20
	v_lshlrev_b32_e32 v149, 16, v100
	v_mul_f32_e32 v149, v36, v149
	v_add_f32_e32 v148, v148, v149
	v_lshlrev_b32_e32 v149, 16, v104
	v_mul_f32_e32 v149, v44, v149
	v_add_f32_e32 v148, v148, v149
	v_mul_f32_e32 v149, v148, v148
	v_fmamk_f32 v149, v149, 0x3dd2d3e8, v224
	v_mul_f32_e32 v149, v148, v149
	v_exp_f32_e32 v149, v149
	s_nop 0
	v_add_f32_e32 v149, 1.0, v149
	v_rcp_f32_e32 v149, v149
	s_nop 0
	v_fma_f32 v148, -v148, v149, v148
	v_lshlrev_b32_e32 v149, 16, v112
	v_mul_f32_e32 v156, v148, v149
	v_and_b32_e32 v148, 0xffff0000, v120
	v_fma_f32 v148, v29, v148, v21
	v_and_b32_e32 v149, 0xffff0000, v100
	v_mul_f32_e32 v149, v37, v149
	v_add_f32_e32 v148, v148, v149
	v_and_b32_e32 v149, 0xffff0000, v104
	v_mul_f32_e32 v149, v45, v149
	v_add_f32_e32 v148, v148, v149
	v_mul_f32_e32 v149, v148, v148
	v_fmamk_f32 v149, v149, 0x3dd2d3e8, v224
	v_mul_f32_e32 v149, v148, v149
	v_exp_f32_e32 v149, v149
	s_nop 0
	v_add_f32_e32 v149, 1.0, v149
	v_rcp_f32_e32 v149, v149
	s_nop 0
	v_fma_f32 v148, -v148, v149, v148
	v_and_b32_e32 v149, 0xffff0000, v112
	v_mul_f32_e32 v148, v148, v149
	v_cvt_pk_bf16_f32 v152, v156, v148
	v_lshlrev_b32_e32 v148, 16, v121
	v_fma_f32 v148, v30, v148, v22
	v_lshlrev_b32_e32 v149, 16, v101
	v_mul_f32_e32 v149, v38, v149
	v_add_f32_e32 v148, v148, v149
	v_lshlrev_b32_e32 v149, 16, v105
	v_mul_f32_e32 v149, v46, v149
	v_add_f32_e32 v148, v148, v149
	v_mul_f32_e32 v149, v148, v148
	v_fmamk_f32 v149, v149, 0x3dd2d3e8, v224
	v_mul_f32_e32 v149, v148, v149
	v_exp_f32_e32 v149, v149
	s_nop 0
	v_add_f32_e32 v149, 1.0, v149
	v_rcp_f32_e32 v149, v149
	s_nop 0
	v_fma_f32 v148, -v148, v149, v148
	v_lshlrev_b32_e32 v149, 16, v113
	v_mul_f32_e32 v156, v148, v149
	v_and_b32_e32 v148, 0xffff0000, v121
	v_fma_f32 v148, v31, v148, v23
	v_and_b32_e32 v149, 0xffff0000, v101
	v_mul_f32_e32 v149, v39, v149
	v_add_f32_e32 v148, v148, v149
	v_and_b32_e32 v149, 0xffff0000, v105
	v_mul_f32_e32 v149, v47, v149
	v_add_f32_e32 v148, v148, v149
	v_mul_f32_e32 v149, v148, v148
	v_fmamk_f32 v149, v149, 0x3dd2d3e8, v224
	v_mul_f32_e32 v149, v148, v149
	v_exp_f32_e32 v149, v149
	s_nop 0
	v_add_f32_e32 v149, 1.0, v149
	v_rcp_f32_e32 v149, v149
	s_nop 0
	v_fma_f32 v148, -v148, v149, v148
	v_and_b32_e32 v149, 0xffff0000, v113
	v_mul_f32_e32 v148, v148, v149
	v_cvt_pk_bf16_f32 v153, v156, v148
	v_lshlrev_b32_e32 v148, 16, v122
	v_fma_f32 v148, v32, v148, v24
	v_lshlrev_b32_e32 v149, 16, v102
	v_mul_f32_e32 v149, v40, v149
	v_add_f32_e32 v148, v148, v149
	v_lshlrev_b32_e32 v149, 16, v106
	v_mul_f32_e32 v149, v48, v149
	v_add_f32_e32 v148, v148, v149
	v_mul_f32_e32 v149, v148, v148
	v_fmamk_f32 v149, v149, 0x3dd2d3e8, v224
	v_mul_f32_e32 v149, v148, v149
	v_exp_f32_e32 v149, v149
	s_nop 0
	v_add_f32_e32 v149, 1.0, v149
	v_rcp_f32_e32 v149, v149
	s_nop 0
	v_fma_f32 v148, -v148, v149, v148
	v_lshlrev_b32_e32 v149, 16, v114
	v_mul_f32_e32 v156, v148, v149
	v_and_b32_e32 v148, 0xffff0000, v122
	v_fma_f32 v148, v33, v148, v25
	v_and_b32_e32 v149, 0xffff0000, v102
	v_mul_f32_e32 v149, v41, v149
	v_add_f32_e32 v148, v148, v149
	v_and_b32_e32 v149, 0xffff0000, v106
	v_mul_f32_e32 v149, v49, v149
	v_add_f32_e32 v148, v148, v149
	v_mul_f32_e32 v149, v148, v148
	v_fmamk_f32 v149, v149, 0x3dd2d3e8, v224
	v_mul_f32_e32 v149, v148, v149
	v_exp_f32_e32 v149, v149
	s_nop 0
	v_add_f32_e32 v149, 1.0, v149
	v_rcp_f32_e32 v149, v149
	s_nop 0
	v_fma_f32 v148, -v148, v149, v148
	v_and_b32_e32 v149, 0xffff0000, v114
	v_mul_f32_e32 v148, v148, v149
	v_cvt_pk_bf16_f32 v154, v156, v148
	v_lshlrev_b32_e32 v148, 16, v123
	v_fma_f32 v148, v34, v148, v26
	v_lshlrev_b32_e32 v149, 16, v103
	v_mul_f32_e32 v149, v42, v149
	v_add_f32_e32 v148, v148, v149
	v_lshlrev_b32_e32 v149, 16, v107
	v_mul_f32_e32 v149, v50, v149
	v_add_f32_e32 v148, v148, v149
	v_mul_f32_e32 v149, v148, v148
	v_fmamk_f32 v149, v149, 0x3dd2d3e8, v224
	v_mul_f32_e32 v149, v148, v149
	v_exp_f32_e32 v149, v149
	s_nop 0
	v_add_f32_e32 v149, 1.0, v149
	v_rcp_f32_e32 v149, v149
	s_nop 0
	v_fma_f32 v148, -v148, v149, v148
	v_lshlrev_b32_e32 v149, 16, v115
	v_mul_f32_e32 v156, v148, v149
	v_and_b32_e32 v148, 0xffff0000, v123
	v_fma_f32 v148, v35, v148, v27
	v_and_b32_e32 v149, 0xffff0000, v103
	v_mul_f32_e32 v149, v43, v149
	v_add_f32_e32 v148, v148, v149
	v_and_b32_e32 v149, 0xffff0000, v107
	v_mul_f32_e32 v149, v51, v149
	v_add_f32_e32 v148, v148, v149
	v_mul_f32_e32 v149, v148, v148
	v_fmamk_f32 v149, v149, 0x3dd2d3e8, v224
	v_mul_f32_e32 v149, v148, v149
	v_exp_f32_e32 v149, v149
	s_nop 0
	v_add_f32_e32 v149, 1.0, v149
	v_rcp_f32_e32 v149, v149
	s_nop 0
	v_fma_f32 v148, -v148, v149, v148
	v_and_b32_e32 v149, 0xffff0000, v115
	v_mul_f32_e32 v148, v148, v149
	v_cvt_pk_bf16_f32 v155, v156, v148
	global_store_dwordx4 v[14:15], v[152:155], off
	v_lshl_add_u64 v[14:15], v[14:15], 0, s[48:49]
	s_nop 0
	v_lshlrev_b32_e32 v148, 16, v140
	v_fma_f32 v148, v28, v148, v20
	v_lshlrev_b32_e32 v149, 16, v144
	v_mul_f32_e32 v149, v36, v149
	v_add_f32_e32 v148, v148, v149
	v_lshlrev_b32_e32 v149, 16, v124
	v_mul_f32_e32 v149, v44, v149
	v_add_f32_e32 v148, v148, v149
	v_mul_f32_e32 v149, v148, v148
	v_fmamk_f32 v149, v149, 0x3dd2d3e8, v224
	v_mul_f32_e32 v149, v148, v149
	v_exp_f32_e32 v149, v149
	s_nop 0
	v_add_f32_e32 v149, 1.0, v149
	v_rcp_f32_e32 v149, v149
	s_nop 0
	v_fma_f32 v148, -v148, v149, v148
	v_lshlrev_b32_e32 v149, 16, v132
	v_mul_f32_e32 v156, v148, v149
	v_and_b32_e32 v148, 0xffff0000, v140
	v_fma_f32 v148, v29, v148, v21
	v_and_b32_e32 v149, 0xffff0000, v144
	v_mul_f32_e32 v149, v37, v149
	v_add_f32_e32 v148, v148, v149
	v_and_b32_e32 v149, 0xffff0000, v124
	v_mul_f32_e32 v149, v45, v149
; __device__ __forceinline__ u32x4 pack8(const float* f) { u32x4 w; w.x = pk2(f[0], f[1]); w.y = pk2(f[2], f[3]); w.z = pk2(f[4], f[5]); w.w = pk2(f[6], f[7]); return w; }
; __device__ __forceinline__ float geluf_(float x) { const float z = x * __builtin_fmaf(x * x, 0.1029432397f, 2.302208198f); const float r = __builtin_amdgcn_rcpf(1.f + __builtin_amdgcn_exp2f(z)); return __builtin_fmaf(-x, r, x); }
; __device__ __forceinline__ void act_fixup(const Params& p, int l, int pm) {
;     ...
;             float g[8], up[8], g1[8], g2[8], o[8];
;             unpack8(rg[k], g); unpack8(ru[k], up); unpack8(r1[k], g1); unpack8(r2[k], g2);
; #pragma unroll
;             for (int e = 0; e < 8; ++e) o[e] = geluf_(cb[c0 + e] + cw[c0 + e] * g2[e] + cw[DFF + c0 + e] * g1[e] + cw[2 * DFF + c0 + e] * g[e]) * up[e];
;             *(u32x4*)(act + ((size_t)blk * 64 + rr) * DFF + c0) = pack8(o);
	v_add_f32_e32 v148, v148, v149
	v_mul_f32_e32 v149, v148, v148
	v_fmamk_f32 v149, v149, 0x3dd2d3e8, v224
	v_mul_f32_e32 v149, v148, v149
	v_exp_f32_e32 v149, v149
	s_nop 0
	v_add_f32_e32 v149, 1.0, v149
	v_rcp_f32_e32 v149, v149
	s_nop 0
	v_fma_f32 v148, -v148, v149, v148
	v_and_b32_e32 v149, 0xffff0000, v132
	v_mul_f32_e32 v148, v148, v149
	v_cvt_pk_bf16_f32 v152, v156, v148
	v_lshlrev_b32_e32 v148, 16, v141
	v_fma_f32 v148, v30, v148, v22
	v_lshlrev_b32_e32 v149, 16, v145
	v_mul_f32_e32 v149, v38, v149
	v_add_f32_e32 v148, v148, v149
	v_lshlrev_b32_e32 v149, 16, v125
	v_mul_f32_e32 v149, v46, v149
	v_add_f32_e32 v148, v148, v149
	v_mul_f32_e32 v149, v148, v148
	v_fmamk_f32 v149, v149, 0x3dd2d3e8, v224
	v_mul_f32_e32 v149, v148, v149
	v_exp_f32_e32 v149, v149
	s_nop 0
	v_add_f32_e32 v149, 1.0, v149
	v_rcp_f32_e32 v149, v149
	s_nop 0
	v_fma_f32 v148, -v148, v149, v148
	v_lshlrev_b32_e32 v149, 16, v133
	v_mul_f32_e32 v156, v148, v149
	v_and_b32_e32 v148, 0xffff0000, v141
	v_fma_f32 v148, v31, v148, v23
	v_and_b32_e32 v149, 0xffff0000, v145
	v_mul_f32_e32 v149, v39, v149
	v_add_f32_e32 v148, v148, v149
	v_and_b32_e32 v149, 0xffff0000, v125
	v_mul_f32_e32 v149, v47, v149
	v_add_f32_e32 v148, v148, v149
	v_mul_f32_e32 v149, v148, v148
	v_fmamk_f32 v149, v149, 0x3dd2d3e8, v224
	v_mul_f32_e32 v149, v148, v149
	v_exp_f32_e32 v149, v149
	s_nop 0
	v_add_f32_e32 v149, 1.0, v149
	v_rcp_f32_e32 v149, v149
	s_nop 0
	v_fma_f32 v148, -v148, v149, v148
	v_and_b32_e32 v149, 0xffff0000, v133
	v_mul_f32_e32 v148, v148, v149
	v_cvt_pk_bf16_f32 v153, v156, v148
	v_lshlrev_b32_e32 v148, 16, v142
	v_fma_f32 v148, v32, v148, v24
	v_lshlrev_b32_e32 v149, 16, v146
	v_mul_f32_e32 v149, v40, v149
	v_add_f32_e32 v148, v148, v149
	v_lshlrev_b32_e32 v149, 16, v126
	v_mul_f32_e32 v149, v48, v149
	v_add_f32_e32 v148, v148, v149
	v_mul_f32_e32 v149, v148, v148
	v_fmamk_f32 v149, v149, 0x3dd2d3e8, v224
	v_mul_f32_e32 v149, v148, v149
	v_exp_f32_e32 v149, v149
	s_nop 0
	v_add_f32_e32 v149, 1.0, v149
	v_rcp_f32_e32 v149, v149
	s_nop 0
	v_fma_f32 v148, -v148, v149, v148
	v_lshlrev_b32_e32 v149, 16, v134
	v_mul_f32_e32 v156, v148, v149
	v_and_b32_e32 v148, 0xffff0000, v142
	v_fma_f32 v148, v33, v148, v25
	v_and_b32_e32 v149, 0xffff0000, v146
	v_mul_f32_e32 v149, v41, v149
	v_add_f32_e32 v148, v148, v149
	v_and_b32_e32 v149, 0xffff0000, v126
	v_mul_f32_e32 v149, v49, v149
	v_add_f32_e32 v148, v148, v149
	v_mul_f32_e32 v149, v148, v148
	v_fmamk_f32 v149, v149, 0x3dd2d3e8, v224
	v_mul_f32_e32 v149, v148, v149
	v_exp_f32_e32 v149, v149
	s_nop 0
	v_add_f32_e32 v149, 1.0, v149
	v_rcp_f32_e32 v149, v149
	s_nop 0
	v_fma_f32 v148, -v148, v149, v148
	v_and_b32_e32 v149, 0xffff0000, v134
	v_mul_f32_e32 v148, v148, v149
	v_cvt_pk_bf16_f32 v154, v156, v148
	v_lshlrev_b32_e32 v148, 16, v143
	v_fma_f32 v148, v34, v148, v26
	v_lshlrev_b32_e32 v149, 16, v147
	v_mul_f32_e32 v149, v42, v149
	v_add_f32_e32 v148, v148, v149
	v_lshlrev_b32_e32 v149, 16, v127
	v_mul_f32_e32 v149, v50, v149
	v_add_f32_e32 v148, v148, v149
	v_mul_f32_e32 v149, v148, v148
	v_fmamk_f32 v149, v149, 0x3dd2d3e8, v224
	v_mul_f32_e32 v149, v148, v149
	v_exp_f32_e32 v149, v149
	s_nop 0
	v_add_f32_e32 v149, 1.0, v149
	v_rcp_f32_e32 v149, v149
	s_nop 0
	v_fma_f32 v148, -v148, v149, v148
	v_lshlrev_b32_e32 v149, 16, v135
	v_mul_f32_e32 v156, v148, v149
	v_and_b32_e32 v148, 0xffff0000, v143
	v_fma_f32 v148, v35, v148, v27
	v_and_b32_e32 v149, 0xffff0000, v147
	v_mul_f32_e32 v149, v43, v149
	v_add_f32_e32 v148, v148, v149
	v_and_b32_e32 v149, 0xffff0000, v127
	v_mul_f32_e32 v149, v51, v149
	v_add_f32_e32 v148, v148, v149
	v_mul_f32_e32 v149, v148, v148
	v_fmamk_f32 v149, v149, 0x3dd2d3e8, v224
	v_mul_f32_e32 v149, v148, v149
	v_exp_f32_e32 v149, v149
	s_nop 0
	v_add_f32_e32 v149, 1.0, v149
	v_rcp_f32_e32 v149, v149
	s_nop 0
	v_fma_f32 v148, -v148, v149, v148
	v_and_b32_e32 v149, 0xffff0000, v135
	v_mul_f32_e32 v148, v148, v149
	v_cvt_pk_bf16_f32 v155, v156, v148
	global_store_dwordx4 v[14:15], v[152:155], off
	v_lshl_add_u64 v[14:15], v[14:15], 0, s[44:45]
	s_nop 0
	v_lshlrev_b32_e32 v148, 16, v144
	v_fma_f32 v148, v28, v148, v20
	v_lshlrev_b32_e32 v149, 16, v124
	v_mul_f32_e32 v149, v36, v149
	v_add_f32_e32 v148, v148, v149
	v_lshlrev_b32_e32 v149, 16, v128
	v_mul_f32_e32 v149, v44, v149
	v_add_f32_e32 v148, v148, v149
	v_mul_f32_e32 v149, v148, v148
	v_fmamk_f32 v149, v149, 0x3dd2d3e8, v224
	v_mul_f32_e32 v149, v148, v149
	v_exp_f32_e32 v149, v149
; __device__ __forceinline__ u32x4 pack8(const float* f) { u32x4 w; w.x = pk2(f[0], f[1]); w.y = pk2(f[2], f[3]); w.z = pk2(f[4], f[5]); w.w = pk2(f[6], f[7]); return w; }
; __device__ __forceinline__ float geluf_(float x) { const float z = x * __builtin_fmaf(x * x, 0.1029432397f, 2.302208198f); const float r = __builtin_amdgcn_rcpf(1.f + __builtin_amdgcn_exp2f(z)); return __builtin_fmaf(-x, r, x); }
; __device__ __forceinline__ void act_fixup(const Params& p, int l, int pm) {
;     ...
;             float g[8], up[8], g1[8], g2[8], o[8];
;             unpack8(rg[k], g); unpack8(ru[k], up); unpack8(r1[k], g1); unpack8(r2[k], g2);
; #pragma unroll
;             for (int e = 0; e < 8; ++e) o[e] = geluf_(cb[c0 + e] + cw[c0 + e] * g2[e] + cw[DFF + c0 + e] * g1[e] + cw[2 * DFF + c0 + e] * g[e]) * up[e];
;             *(u32x4*)(act + ((size_t)blk * 64 + rr) * DFF + c0) = pack8(o);
	s_nop 0
	v_add_f32_e32 v149, 1.0, v149
	v_rcp_f32_e32 v149, v149
	s_nop 0
	v_fma_f32 v148, -v148, v149, v148
	v_lshlrev_b32_e32 v149, 16, v136
	v_mul_f32_e32 v156, v148, v149
	v_and_b32_e32 v148, 0xffff0000, v144
	v_fma_f32 v148, v29, v148, v21
	v_and_b32_e32 v149, 0xffff0000, v124
	v_mul_f32_e32 v149, v37, v149
	v_add_f32_e32 v148, v148, v149
	v_and_b32_e32 v149, 0xffff0000, v128
	v_mul_f32_e32 v149, v45, v149
	v_add_f32_e32 v148, v148, v149
	v_mul_f32_e32 v149, v148, v148
	v_fmamk_f32 v149, v149, 0x3dd2d3e8, v224
	v_mul_f32_e32 v149, v148, v149
	v_exp_f32_e32 v149, v149
	s_nop 0
	v_add_f32_e32 v149, 1.0, v149
	v_rcp_f32_e32 v149, v149
	s_nop 0
	v_fma_f32 v148, -v148, v149, v148
	v_and_b32_e32 v149, 0xffff0000, v136
	v_mul_f32_e32 v148, v148, v149
	v_cvt_pk_bf16_f32 v152, v156, v148
	v_lshlrev_b32_e32 v148, 16, v145
	v_fma_f32 v148, v30, v148, v22
	v_lshlrev_b32_e32 v149, 16, v125
	v_mul_f32_e32 v149, v38, v149
	v_add_f32_e32 v148, v148, v149
	v_lshlrev_b32_e32 v149, 16, v129
	v_mul_f32_e32 v149, v46, v149
	v_add_f32_e32 v148, v148, v149
	v_mul_f32_e32 v149, v148, v148
	v_fmamk_f32 v149, v149, 0x3dd2d3e8, v224
	v_mul_f32_e32 v149, v148, v149
	v_exp_f32_e32 v149, v149
	s_nop 0
	v_add_f32_e32 v149, 1.0, v149
	v_rcp_f32_e32 v149, v149
	s_nop 0
	v_fma_f32 v148, -v148, v149, v148
	v_lshlrev_b32_e32 v149, 16, v137
	v_mul_f32_e32 v156, v148, v149
	v_and_b32_e32 v148, 0xffff0000, v145
	v_fma_f32 v148, v31, v148, v23
	v_and_b32_e32 v149, 0xffff0000, v125
	v_mul_f32_e32 v149, v39, v149
	v_add_f32_e32 v148, v148, v149
	v_and_b32_e32 v149, 0xffff0000, v129
	v_mul_f32_e32 v149, v47, v149
	v_add_f32_e32 v148, v148, v149
	v_mul_f32_e32 v149, v148, v148
	v_fmamk_f32 v149, v149, 0x3dd2d3e8, v224
	v_mul_f32_e32 v149, v148, v149
	v_exp_f32_e32 v149, v149
	s_nop 0
	v_add_f32_e32 v149, 1.0, v149
	v_rcp_f32_e32 v149, v149
	s_nop 0
	v_fma_f32 v148, -v148, v149, v148
	v_and_b32_e32 v149, 0xffff0000, v137
	v_mul_f32_e32 v148, v148, v149
	v_cvt_pk_bf16_f32 v153, v156, v148
	v_lshlrev_b32_e32 v148, 16, v146
	v_fma_f32 v148, v32, v148, v24
	v_lshlrev_b32_e32 v149, 16, v126
	v_mul_f32_e32 v149, v40, v149
	v_add_f32_e32 v148, v148, v149
	v_lshlrev_b32_e32 v149, 16, v130
	v_mul_f32_e32 v149, v48, v149
	v_add_f32_e32 v148, v148, v149
	v_mul_f32_e32 v149, v148, v148
	v_fmamk_f32 v149, v149, 0x3dd2d3e8, v224
	v_mul_f32_e32 v149, v148, v149
	v_exp_f32_e32 v149, v149
	s_nop 0
	v_add_f32_e32 v149, 1.0, v149
	v_rcp_f32_e32 v149, v149
	s_nop 0
	v_fma_f32 v148, -v148, v149, v148
	v_lshlrev_b32_e32 v149, 16, v138
	v_mul_f32_e32 v156, v148, v149
	v_and_b32_e32 v148, 0xffff0000, v146
	v_fma_f32 v148, v33, v148, v25
	v_and_b32_e32 v149, 0xffff0000, v126
	v_mul_f32_e32 v149, v41, v149
	v_add_f32_e32 v148, v148, v149
	v_and_b32_e32 v149, 0xffff0000, v130
	v_mul_f32_e32 v149, v49, v149
	v_add_f32_e32 v148, v148, v149
	v_mul_f32_e32 v149, v148, v148
	v_fmamk_f32 v149, v149, 0x3dd2d3e8, v224
	v_mul_f32_e32 v149, v148, v149
	v_exp_f32_e32 v149, v149
	s_nop 0
	v_add_f32_e32 v149, 1.0, v149
	v_rcp_f32_e32 v149, v149
	s_nop 0
	v_fma_f32 v148, -v148, v149, v148
	v_and_b32_e32 v149, 0xffff0000, v138
	v_mul_f32_e32 v148, v148, v149
	v_cvt_pk_bf16_f32 v154, v156, v148
	v_lshlrev_b32_e32 v148, 16, v147
	v_fma_f32 v148, v34, v148, v26
	v_lshlrev_b32_e32 v149, 16, v127
	v_mul_f32_e32 v149, v42, v149
	v_add_f32_e32 v148, v148, v149
	v_lshlrev_b32_e32 v149, 16, v131
	v_mul_f32_e32 v149, v50, v149
	v_add_f32_e32 v148, v148, v149
	v_mul_f32_e32 v149, v148, v148
	v_fmamk_f32 v149, v149, 0x3dd2d3e8, v224
	v_mul_f32_e32 v149, v148, v149
	v_exp_f32_e32 v149, v149
	s_nop 0
	v_add_f32_e32 v149, 1.0, v149
	v_rcp_f32_e32 v149, v149
	s_nop 0
	v_fma_f32 v148, -v148, v149, v148
	v_lshlrev_b32_e32 v149, 16, v139
	v_mul_f32_e32 v156, v148, v149
	v_and_b32_e32 v148, 0xffff0000, v147
	v_fma_f32 v148, v35, v148, v27
	v_and_b32_e32 v149, 0xffff0000, v127
	v_mul_f32_e32 v149, v43, v149
	v_add_f32_e32 v148, v148, v149
	v_and_b32_e32 v149, 0xffff0000, v131
	v_mul_f32_e32 v149, v51, v149
	v_add_f32_e32 v148, v148, v149
	v_mul_f32_e32 v149, v148, v148
	v_fmamk_f32 v149, v149, 0x3dd2d3e8, v224
	v_mul_f32_e32 v149, v148, v149
	v_exp_f32_e32 v149, v149
	s_nop 0
	v_add_f32_e32 v149, 1.0, v149
	v_rcp_f32_e32 v149, v149
	s_nop 0
	v_fma_f32 v148, -v148, v149, v148
	v_and_b32_e32 v149, 0xffff0000, v139
	v_mul_f32_e32 v148, v148, v149
	v_cvt_pk_bf16_f32 v155, v156, v148
	global_store_dwordx4 v[14:15], v[152:155], off
	s_branch .LBB0_56

; #define MFMA(X, Y, C) __builtin_amdgcn_mfma_f32_16x16x32_bf16((X), (Y), (C), 0, 0, 0)
; template <int K, int MODE  >
; __device__ __forceinline__ void thin_gemm(LAS unsigned char* lds, const bf16_t* A, const bf16_t* Bt, int N, void* out, int ldc, bf16_t* xb, u64* rss) {
;     ...
;         for (int i = 0; i < nr; ++i) {
;             const int t = base + i, ct = t >> 3, rt = t & 7;
;             const bf16_t* ap = A + (size_t)(rt * 16 + fr) * K + wid * KW + 8 * fq;
;             const bf16_t* bp = Bt + (size_t)(ct * 16 + fr) * K + wid * KW + 8 * fq;
;             bf16x8 a[STEPS], b[STEPS];
; #pragma unroll
;             for (int s = 0; s < STEPS; ++s) { a[s] = *(const bf16x8*)(ap + 32 * s); b[s] = *(const bf16x8*)(bp + 32 * s); }
;             f32x4 acc = {0.f, 0.f, 0.f, 0.f};
; #pragma unroll
;             for (int s = 0; s < STEPS; ++s) acc = MFMA(b[s], a[s], acc);
;             red[(i * 8 + wid) * 64 + lane] = acc;
.LBB0_197:
	s_and_b32 s41, s30, 0x70
	v_and_or_b32 v0, s40, -16, v7
	s_nop 2
	v_or_b32_e32 v14, s41, v7
	v_mad_i64_i32 v[58:59], s[42:43], v0, s44, v[4:5]
	v_mul_u32_u24_e32 v0, 0xb00, v14
	v_lshlrev_b32_e32 v0, 1, v0
	v_lshl_add_u64 v[60:61], v[2:3], 0, v[0:1]
	global_load_dwordx4 v[14:17], v[58:59], off
	s_waitcnt lgkmcnt(0)
	global_load_dwordx4 v[18:21], v[58:59], off offset:64
	global_load_dwordx4 v[22:25], v[58:59], off offset:128
	global_load_dwordx4 v[26:29], v[58:59], off offset:192
	global_load_dwordx4 v[30:33], v[58:59], off offset:256
	global_load_dwordx4 v[34:37], v[58:59], off offset:320
	global_load_dwordx4 v[38:41], v[58:59], off offset:384
	global_load_dwordx4 v[42:45], v[58:59], off offset:448
	global_load_dwordx4 v[46:49], v[58:59], off offset:512
	global_load_dwordx4 v[50:53], v[58:59], off offset:576
	global_load_dwordx4 v[54:57], v[58:59], off offset:640
	global_load_dwordx4 v[64:67], v[60:61], off
	global_load_dwordx4 v[68:71], v[60:61], off offset:64
	global_load_dwordx4 v[72:75], v[60:61], off offset:128
	global_load_dwordx4 v[76:79], v[60:61], off offset:192
	global_load_dwordx4 v[80:83], v[60:61], off offset:256
	global_load_dwordx4 v[84:87], v[60:61], off offset:320
	global_load_dwordx4 v[88:91], v[60:61], off offset:384
	global_load_dwordx4 v[92:95], v[60:61], off offset:448
	global_load_dwordx4 v[96:99], v[60:61], off offset:512
	global_load_dwordx4 v[100:103], v[60:61], off offset:576
	global_load_dwordx4 v[104:107], v[60:61], off offset:640
	s_addk_i32 s1, 0xe000
	s_add_i32 s40, s40, 2
	s_add_i32 s30, s30, 16
	s_cmp_eq_u32 s1, 0
	s_waitcnt vmcnt(10)
	v_mfma_f32_16x16x32_bf16 v[14:17], v[14:17], v[64:67], 0
	s_waitcnt vmcnt(9)
	v_mfma_f32_16x16x32_bf16 v[14:17], v[18:21], v[68:71], v[14:17]
	s_waitcnt vmcnt(8)
	v_mfma_f32_16x16x32_bf16 v[14:17], v[22:25], v[72:75], v[14:17]
	s_waitcnt vmcnt(7)
	v_mfma_f32_16x16x32_bf16 v[14:17], v[26:29], v[76:79], v[14:17]
	s_waitcnt vmcnt(6)
	v_mfma_f32_16x16x32_bf16 v[14:17], v[30:33], v[80:83], v[14:17]
	s_waitcnt vmcnt(5)
	v_mfma_f32_16x16x32_bf16 v[14:17], v[34:37], v[84:87], v[14:17]
	s_waitcnt vmcnt(4)
	v_mfma_f32_16x16x32_bf16 v[14:17], v[38:41], v[88:91], v[14:17]
	s_waitcnt vmcnt(3)
	v_mfma_f32_16x16x32_bf16 v[14:17], v[42:45], v[92:95], v[14:17]
	s_waitcnt vmcnt(2)
	v_mfma_f32_16x16x32_bf16 v[14:17], v[46:49], v[96:99], v[14:17]
	s_waitcnt vmcnt(1)
	v_mfma_f32_16x16x32_bf16 v[14:17], v[50:53], v[100:103], v[14:17]
	s_waitcnt vmcnt(0)
	v_mfma_f32_16x16x32_bf16 v[14:17], v[54:57], v[104:107], v[14:17]
	s_nop 7
	ds_write_b128 v13, v[14:17]
	v_add_u32_e32 v13, 0x2000, v13
	s_cbranch_scc0 .LBB0_197

; #define MFMA(X, Y, C) __builtin_amdgcn_mfma_f32_16x16x32_bf16((X), (Y), (C), 0, 0, 0)
; template <int K, int MODE  >
; __device__ __forceinline__ void thin_gemm(LAS unsigned char* lds, const bf16_t* A, const bf16_t* Bt, int N, void* out, int ldc, bf16_t* xb, u64* rss) {
;     ...
;         for (int i = 0; i < nr; ++i) {
;             const int t = base + i, ct = t >> 3, rt = t & 7;
;             const bf16_t* ap = A + (size_t)(rt * 16 + fr) * K + wid * KW + 8 * fq;
;             const bf16_t* bp = Bt + (size_t)(ct * 16 + fr) * K + wid * KW + 8 * fq;
;             bf16x8 a[STEPS], b[STEPS];
; #pragma unroll
;             for (int s = 0; s < STEPS; ++s) { a[s] = *(const bf16x8*)(ap + 32 * s); b[s] = *(const bf16x8*)(bp + 32 * s); }
;             f32x4 acc = {0.f, 0.f, 0.f, 0.f};
; #pragma unroll
;             for (int s = 0; s < STEPS; ++s) acc = MFMA(b[s], a[s], acc);
;             red[(i * 8 + wid) * 64 + lane] = acc;
.LBB0_291:
	s_and_b32 s37, s30, 0x70
	v_and_or_b32 v0, s36, -16, v7
	s_nop 2
	v_or_b32_e32 v14, s37, v7
	v_mad_i64_i32 v[34:35], s[40:41], v0, s43, v[4:5]
	v_mul_u32_u24_e32 v0, 0x600, v14
	v_lshlrev_b32_e32 v0, 1, v0
	v_lshl_add_u64 v[42:43], v[2:3], 0, v[0:1]
	global_load_dwordx4 v[14:17], v[34:35], off
	s_waitcnt lgkmcnt(0)
	global_load_dwordx4 v[18:21], v[34:35], off offset:64
	global_load_dwordx4 v[22:25], v[34:35], off offset:128
	global_load_dwordx4 v[26:29], v[34:35], off offset:192
	global_load_dwordx4 v[30:33], v[34:35], off offset:256
	global_load_dwordx4 v[38:41], v[42:43], off
	global_load_dwordx4 v[44:47], v[42:43], off offset:64
	global_load_dwordx4 v[48:51], v[42:43], off offset:128
	global_load_dwordx4 v[52:55], v[42:43], off offset:192
	global_load_dwordx4 v[56:59], v[42:43], off offset:256
	global_load_dwordx4 v[60:63], v[42:43], off offset:320
	global_load_dwordx4 v[34:37], v[34:35], off offset:320
	s_addk_i32 s1, 0xe000
	s_add_i32 s36, s36, 2
	s_add_i32 s30, s30, 16
	s_cmp_eq_u32 s1, 0
	s_waitcnt vmcnt(6)
	v_mfma_f32_16x16x32_bf16 v[14:17], v[14:17], v[38:41], 0
	s_waitcnt vmcnt(5)
	v_mfma_f32_16x16x32_bf16 v[14:17], v[18:21], v[44:47], v[14:17]
	s_waitcnt vmcnt(4)
	v_mfma_f32_16x16x32_bf16 v[14:17], v[22:25], v[48:51], v[14:17]
	s_waitcnt vmcnt(3)
	v_mfma_f32_16x16x32_bf16 v[14:17], v[26:29], v[52:55], v[14:17]
	s_waitcnt vmcnt(2)
	v_mfma_f32_16x16x32_bf16 v[14:17], v[30:33], v[56:59], v[14:17]
	s_waitcnt vmcnt(0)
	v_mfma_f32_16x16x32_bf16 v[14:17], v[34:37], v[60:63], v[14:17]
	s_nop 7
	ds_write_b128 v13, v[14:17]
	v_add_u32_e32 v13, 0x2000, v13
	s_cbranch_scc0 .LBB0_291

; #define MFMA(X, Y, C) __builtin_amdgcn_mfma_f32_16x16x32_bf16((X), (Y), (C), 0, 0, 0)
; template <int K, int MODE  >
; __device__ __forceinline__ void thin_gemm(LAS unsigned char* lds, const bf16_t* A, const bf16_t* Bt, int N, void* out, int ldc, bf16_t* xb, u64* rss) {
;     ...
;         for (int i = 0; i < nr; ++i) {
;             const int t = base + i, ct = t >> 3, rt = t & 7;
;             const bf16_t* ap = A + (size_t)(rt * 16 + fr) * K + wid * KW + 8 * fq;
;             const bf16_t* bp = Bt + (size_t)(ct * 16 + fr) * K + wid * KW + 8 * fq;
;             bf16x8 a[STEPS], b[STEPS];
; #pragma unroll
;             for (int s = 0; s < STEPS; ++s) { a[s] = *(const bf16x8*)(ap + 32 * s); b[s] = *(const bf16x8*)(bp + 32 * s); }
;             f32x4 acc = {0.f, 0.f, 0.f, 0.f};
; #pragma unroll
;             for (int s = 0; s < STEPS; ++s) acc = MFMA(b[s], a[s], acc);
;             red[(i * 8 + wid) * 64 + lane] = acc;
.LBB0_522:
	v_and_or_b32 v8, s36, -16, v11
	s_and_b32 s37, s30, 0x70
	v_ashrrev_i32_e32 v9, 31, v8
	v_or_b32_e32 v0, s37, v11
	v_lshlrev_b64 v[8:9], 11, v[8:9]
	v_lshlrev_b32_e32 v0, 11, v0
	v_lshl_add_u64 v[8:9], v[4:5], 0, v[8:9]
	v_lshl_add_u64 v[36:37], v[2:3], 0, v[0:1]
	global_load_dwordx4 v[16:19], v[8:9], off
	s_waitcnt lgkmcnt(0)
	global_load_dwordx4 v[24:27], v[8:9], off offset:64
	global_load_dwordx4 v[32:35], v[8:9], off offset:128
	global_load_dwordx4 v[40:43], v[8:9], off offset:192
	global_load_dwordx4 v[20:23], v[36:37], off
	global_load_dwordx4 v[28:31], v[36:37], off offset:64
	global_load_dwordx4 v[44:47], v[36:37], off offset:128
	global_load_dwordx4 v[48:51], v[36:37], off offset:192
	s_addk_i32 s23, 0xe000
	s_add_i32 s36, s36, 2
	s_add_i32 s30, s30, 16
	s_cmp_eq_u32 s23, 0
	s_waitcnt vmcnt(3)
	v_mfma_f32_16x16x32_bf16 v[16:19], v[16:19], v[20:23], 0
	s_waitcnt vmcnt(2)
	v_mfma_f32_16x16x32_bf16 v[16:19], v[24:27], v[28:31], v[16:19]
	s_waitcnt vmcnt(1)
	v_mfma_f32_16x16x32_bf16 v[16:19], v[32:35], v[44:47], v[16:19]
	s_waitcnt vmcnt(0)
	v_mfma_f32_16x16x32_bf16 v[16:19], v[40:43], v[48:51], v[16:19]
	s_nop 7
	ds_write_b128 v6, v[16:19]
	v_add_u32_e32 v6, 0x2000, v6
	s_cbranch_scc0 .LBB0_522

; #define LAS __attribute__((address_space(3)))
; __device__ __forceinline__ u32x4 pack8(const float* f) { u32x4 w; w.x = pk2(f[0], f[1]); w.y = pk2(f[2], f[3]); w.z = pk2(f[4], f[5]); w.w = pk2(f[6], f[7]); return w; }
; __device__ void phase_prep(const Params& p, LAS unsigned char* lds) {
;     ...
;             for (int ps = 0; ps < 2; ++ps) { v[q][ps] = __builtin_nontemporal_load((const f32x4*)(src[q] + (size_t)((tid >> 4) + ps * 32) * ldns[q] + (tid & 15) * 4)); if (gs[q]) v[q][ps] = v[q][ps] * gs[q][kt * 64 + (tid >> 4) + ps * 32]; }
;         }
; #pragma unroll
;         for (int q = 0; q < 4; ++q)
; #pragma unroll
;             for (int ps = 0; ps < 2; ++ps) { LAS float* t = tl + q * 4160 + ((tid >> 4) + ps * 32) * 65 + (tid & 15) * 4; t[0] = v[q][ps][0]; t[1] = v[q][ps][1]; t[2] = v[q][ps][2]; t[3] = v[q][ps][3]; }
;         __syncthreads();
; #pragma unroll
;         for (int q = 0; q < 4; ++q) {
;             const int n = tid >> 3, kq = tid & 7;
;             float f[8];
; #pragma unroll
;             for (int e = 0; e < 8; ++e) f[e] = tl[q * 4160 + (8 * kq + e) * 65 + n];
;             *(u32x4*)(dst[q] + (size_t)n * Ks[q] + 8 * kq) = pack8(f);
;         }
;         __syncthreads();
.LBB0_528:
	s_waitcnt vmcnt(0)
	v_pk_mul_f32 v[4:5], v[4:5], v[100:101] op_sel_hi:[1,0]
	v_pk_mul_f32 v[2:3], v[2:3], v[100:101] op_sel_hi:[1,0]
	v_pk_mul_f32 v[8:9], v[8:9], v[102:103] op_sel_hi:[1,0]
	v_pk_mul_f32 v[6:7], v[6:7], v[102:103] op_sel_hi:[1,0]
	v_pk_mul_f32 v[12:13], v[12:13], v[104:105] op_sel_hi:[1,0]
	v_pk_mul_f32 v[10:11], v[10:11], v[104:105] op_sel_hi:[1,0]
	v_pk_mul_f32 v[16:17], v[16:17], v[106:107] op_sel_hi:[1,0]
	v_pk_mul_f32 v[14:15], v[14:15], v[106:107] op_sel_hi:[1,0]
	v_pk_mul_f32 v[20:21], v[20:21], v[108:109] op_sel_hi:[1,0]
	v_pk_mul_f32 v[18:19], v[18:19], v[108:109] op_sel_hi:[1,0]
	v_pk_mul_f32 v[24:25], v[24:25], v[110:111] op_sel_hi:[1,0]
	v_pk_mul_f32 v[22:23], v[22:23], v[110:111] op_sel_hi:[1,0]
	v_pk_mul_f32 v[28:29], v[28:29], v[112:113] op_sel_hi:[1,0]
	v_pk_mul_f32 v[26:27], v[26:27], v[112:113] op_sel_hi:[1,0]
	v_pk_mul_f32 v[32:33], v[32:33], v[114:115] op_sel_hi:[1,0]
	v_pk_mul_f32 v[30:31], v[30:31], v[114:115] op_sel_hi:[1,0]
	s_ashr_i32 s54, s62, 31
	s_mul_hi_u32 s55, s50, s62
	s_mul_i32 s54, s50, s54
	s_add_i32 s54, s55, s54
	s_mul_i32 s55, s51, s62
	s_add_i32 s55, s54, s55
	s_mul_i32 s54, s50, s62
	s_lshl_b64 s[54:55], s[54:55], 1
	s_add_u32 s54, s52, s54
	s_addc_u32 s55, s53, s55
	s_lshl_b64 s[52:53], s[58:59], 1
	s_add_u32 s52, s54, s52
	s_addc_u32 s53, s55, s53
	s_ashr_i32 s54, s30, 31
	s_mul_hi_u32 s55, s44, s30
	s_mul_i32 s54, s44, s54
	s_add_i32 s54, s55, s54
	s_mul_i32 s55, s45, s30
	s_add_i32 s55, s54, s55
	s_mul_i32 s54, s44, s30
	s_lshl_b64 s[54:55], s[54:55], 1
	s_waitcnt vmcnt(7)
	ds_write2_b32 v45, v2, v3 offset1:1
	ds_write2_b32 v45, v4, v5 offset0:2 offset1:3
	v_add_u32_e32 v2, 0x2080, v45
	s_add_u32 s30, s46, s54
	s_waitcnt vmcnt(6)
	ds_write2_b32 v2, v6, v7 offset1:1
	v_add_u32_e32 v2, 0x2088, v45
	s_addc_u32 s54, s47, s55
	s_lshl_b64 s[46:47], s[48:49], 1
	ds_write2_b32 v2, v8, v9 offset1:1
	v_add_u32_e32 v2, 0x4100, v45
	s_add_u32 s46, s30, s46
	s_waitcnt vmcnt(5)
	ds_write2_b32 v2, v10, v11 offset1:1
	v_add_u32_e32 v2, 0x4108, v45
	s_addc_u32 s47, s54, s47
	s_ashr_i32 s30, s26, 31
	ds_write2_b32 v2, v12, v13 offset1:1
	v_add_u32_e32 v2, 0x6180, v45
	s_mul_hi_u32 s48, s38, s26
	s_mul_i32 s30, s38, s30
	s_waitcnt vmcnt(4)
	ds_write2_b32 v2, v14, v15 offset1:1
	v_add_u32_e32 v2, 0x6188, v45
	s_add_i32 s30, s48, s30
	s_mul_i32 s48, s39, s26
	ds_write2_b32 v2, v16, v17 offset1:1
	v_add_u32_e32 v2, 0x8200, v45
	s_add_i32 s49, s30, s48
	s_mul_i32 s48, s38, s26
	s_waitcnt vmcnt(3)
	ds_write2_b32 v2, v18, v19 offset1:1
	v_add_u32_e32 v2, 0x8208, v45
	s_lshl_b64 s[48:49], s[48:49], 1
	ds_write2_b32 v2, v20, v21 offset1:1
	v_add_u32_e32 v2, 0xa280, v45
	s_add_u32 s26, s40, s48
	s_waitcnt vmcnt(2)
	ds_write2_b32 v2, v22, v23 offset1:1
	v_add_u32_e32 v2, 0xa288, v45
	s_addc_u32 s30, s41, s49
	s_lshl_b64 s[40:41], s[42:43], 1
	ds_write2_b32 v2, v24, v25 offset1:1
	v_add_u32_e32 v2, 0xc300, v45
	s_add_u32 s40, s26, s40
	s_waitcnt vmcnt(1)
	ds_write2_b32 v2, v26, v27 offset1:1
	v_add_u32_e32 v2, 0xc308, v45
	s_addc_u32 s41, s30, s41
	s_ashr_i32 s26, s24, 31
	ds_write2_b32 v2, v28, v29 offset1:1
	v_add_u32_e32 v2, 0xe380, v45
	s_mul_hi_u32 s30, s22, s24
	s_mul_i32 s26, s22, s26
	s_waitcnt vmcnt(0)
	ds_write2_b32 v2, v30, v31 offset1:1
	v_add_u32_e32 v2, 0xe388, v45
	v_add_u32_e32 v8, 0x400, v46
	s_add_i32 s26, s30, s26
	s_mul_i32 s30, s23, s24
	ds_write2_b32 v2, v32, v33 offset1:1
	s_waitcnt lgkmcnt(0)
	s_barrier
	ds_read2_b32 v[2:3], v46 offset1:65
	ds_read2_b32 v[4:5], v46 offset0:130 offset1:195
	ds_read2_b32 v[6:7], v8 offset0:4 offset1:69
	ds_read2_b32 v[8:9], v8 offset0:134 offset1:199
	s_add_i32 s43, s26, s30
	s_mul_i32 s42, s22, s24
	s_lshl_b64 s[42:43], s[42:43], 1
	s_add_u32 s24, s0, s42
	s_addc_u32 s26, s1, s43
	s_lshl_b64 s[0:1], s[36:37], 1
	s_add_u32 s0, s24, s0
	s_waitcnt lgkmcnt(3)
	v_cvt_pk_bf16_f32 v2, v2, v3
	s_waitcnt lgkmcnt(2)
	v_cvt_pk_bf16_f32 v3, v4, v5
	s_waitcnt lgkmcnt(1)
	v_cvt_pk_bf16_f32 v4, v6, v7
	s_waitcnt lgkmcnt(0)
	v_cvt_pk_bf16_f32 v5, v8, v9
	v_mul_lo_u32 v8, s23, v36
	v_mul_lo_u32 v9, s22, v35
	v_mad_u64_u32 v[6:7], s[22:23], s22, v36, 0
	s_addc_u32 s1, s26, s1
	v_add3_u32 v7, v7, v9, v8
	v_lshl_add_u64 v[6:7], v[6:7], 1, s[0:1]
	v_mov_b32_e32 v41, v1
	v_add_u32_e32 v8, 0x4000, v46
	v_lshl_add_u64 v[6:7], v[6:7], 0, v[40:41]
	ds_read2_b32 v[8:9], v8 offset0:64 offset1:129
	v_add_u32_e32 v10, 0x4200, v46
	v_add_u32_e32 v12, 0x4400, v46
	v_add_u32_e32 v14, 0x4600, v46
	ds_read2_b32 v[10:11], v10 offset0:66 offset1:131
	ds_read2_b32 v[12:13], v12 offset0:68 offset1:133
	ds_read2_b32 v[14:15], v14 offset0:70 offset1:135
	global_store_dwordx4 v[6:7], v[2:5], off
	v_mad_u64_u32 v[6:7], s[0:1], s38, v36, 0
	s_waitcnt lgkmcnt(3)
	v_cvt_pk_bf16_f32 v2, v8, v9
	v_mul_lo_u32 v8, s39, v36
	v_mul_lo_u32 v9, s38, v35
	s_waitcnt lgkmcnt(2)
	v_cvt_pk_bf16_f32 v3, v10, v11
	s_waitcnt lgkmcnt(1)
	v_cvt_pk_bf16_f32 v4, v12, v13
	v_add3_u32 v7, v7, v9, v8
	v_add_u32_e32 v8, 0x8000, v46
	v_add_u32_e32 v12, 0x8400, v46
	s_waitcnt lgkmcnt(0)
	v_cvt_pk_bf16_f32 v5, v14, v15
	v_lshl_add_u64 v[6:7], v[6:7], 1, s[40:41]
	ds_read2_b32 v[8:9], v8 offset0:128 offset1:193
	ds_read2_b32 v[10:11], v12 offset0:2 offset1:67
	ds_read2_b32 v[12:13], v12 offset0:132 offset1:197
	v_lshl_add_u64 v[6:7], v[6:7], 0, v[40:41]
	v_add_u32_e32 v14, 0x8800, v46
	ds_read2_b32 v[14:15], v14 offset0:6 offset1:71
	global_store_dwordx4 v[6:7], v[2:5], off
	v_mad_u64_u32 v[6:7], s[0:1], s44, v36, 0
	s_waitcnt lgkmcnt(3)
	v_cvt_pk_bf16_f32 v2, v8, v9
	v_mul_lo_u32 v8, s45, v36
	v_mul_lo_u32 v9, s44, v35
	v_add3_u32 v7, v7, v9, v8
	v_lshl_add_u64 v[6:7], v[6:7], 1, s[46:47]
	v_add_u32_e32 v8, 0xc200, v46
	s_waitcnt lgkmcnt(2)
	v_cvt_pk_bf16_f32 v3, v10, v11
	s_waitcnt lgkmcnt(1)
	v_cvt_pk_bf16_f32 v4, v12, v13
	s_waitcnt lgkmcnt(0)
	v_cvt_pk_bf16_f32 v5, v14, v15
	v_lshl_add_u64 v[6:7], v[6:7], 0, v[40:41]
	ds_read2_b32 v[8:9], v8 offset0:64 offset1:129
	v_add_u32_e32 v10, 0xc400, v46
	v_add_u32_e32 v12, 0xc600, v46
	v_add_u32_e32 v14, 0xc800, v46
	ds_read2_b32 v[10:11], v10 offset0:66 offset1:131
	ds_read2_b32 v[12:13], v12 offset0:68 offset1:133
	ds_read2_b32 v[14:15], v14 offset0:70 offset1:135
	global_store_dwordx4 v[6:7], v[2:5], off
	v_mad_u64_u32 v[6:7], s[0:1], s50, v36, 0
	s_waitcnt lgkmcnt(3)
	v_cvt_pk_bf16_f32 v2, v8, v9
	v_mul_lo_u32 v8, s51, v36
	v_mul_lo_u32 v9, s50, v35
	v_add3_u32 v7, v7, v9, v8
	v_readlane_b32 s0, v253, 22
	v_readlane_b32 s84, v254, 44
	v_lshl_add_u64 v[6:7], v[6:7], 1, s[52:53]
	s_add_i32 s3, s3, s94
	s_add_i32 s2, s2, s0
	v_readlane_b32 s85, v254, 45
	v_lshl_add_u64 v[6:7], v[6:7], 0, v[40:41]
	s_cmpk_gt_i32 s3, 0xdbf
	s_waitcnt lgkmcnt(2)
	v_cvt_pk_bf16_f32 v3, v10, v11
	s_waitcnt lgkmcnt(1)
	v_cvt_pk_bf16_f32 v4, v12, v13
	s_waitcnt lgkmcnt(0)
	v_cvt_pk_bf16_f32 v5, v14, v15
	global_store_dwordx4 v[6:7], v[2:5], off
	s_barrier
	s_cbranch_scc1 .LBB0_602

; __device__ void phase_prep(const Params& p, LAS unsigned char* lds) {
;     ...
;         for (int q = 0; q < 4; ++q) {
;             const int idx = grp * 4 + q;
;             const int l = idx / 3520; int r = idx % 3520;
;             int kt, nt;
;             if (r < 1024) { gs[q] = p.in[8] + l * DM; src[q] = p.in[9] + (size_t)l * DM * DIN; ldns[q] = DIN; Ks[q] = DM; dst[q] = (bf16_t*)(p.ws + W_WIN) + (size_t)l * NPROJ * DM; nt = r % 64; kt = r / 64; }
;             else if (r < 1408) { r -= 1024; gs[q] = nullptr; src[q] = p.in[24] + (size_t)l * DMIX * DM; ldns[q] = DM; Ks[q] = DMIX; dst[q] = (bf16_t*)(p.ws + W_WOUT) + (size_t)l * DM * DMIX; nt = r % 16; kt = r / 16; }
;             else if (r < 2816) { r -= 1408; gs[q] = p.in[25] + l * DM; src[q] = p.in[26] + (size_t)l * DM * DGU; ldns[q] = DGU; Ks[q] = DM; dst[q] = (bf16_t*)(p.ws + W_WUP) + (size_t)l * DGU * DM; nt = r % 88; kt = r / 88; }
;             else { r -= 2816; gs[q] = nullptr; src[q] = p.in[29] + (size_t)l * DFF * DM; ldns[q] = DM; Ks[q] = DFF; dst[q] = (bf16_t*)(p.ws + W_WDOWN) + (size_t)l * DM * DFF; nt = r % 16; kt = r / 16; }
;             int drow = nt * 64;
;             if (ldns[q] == DGU) { const int f = drow < DFF ? drow : drow - DFF; drow = 256 * (f >> 7) + (f & 127) + (drow < DFF ? 0 : 128); }
;             src[q] += (size_t)(kt * 64) * ldns[q] + nt * 64; dst[q] += (size_t)drow * Ks[q] + kt * 64;
; #pragma unroll
;             for (int ps = 0; ps < 2; ++ps) { v[q][ps] = __builtin_nontemporal_load((const f32x4*)(src[q] + (size_t)((tid >> 4) + ps * 32) * ldns[q] + (tid & 15) * 4)); if (gs[q]) v[q][ps] = v[q][ps] * gs[q][kt * 64 + (tid >> 4) + ps * 32]; }
;         }
.LBB0_533:
	s_lshl_b32 s36, s26, 6
	s_ashr_i32 s37, s36, 31
	s_mul_i32 s26, s42, s37
	s_mul_hi_u32 s30, s42, s36
	s_add_i32 s26, s30, s26
	s_mul_i32 s30, s43, s36
	s_add_i32 s45, s26, s30
	s_mul_i32 s44, s42, s36
	s_ashr_i32 s47, s46, 31
	s_lshl_b64 s[44:45], s[44:45], 2
	s_add_u32 s26, s40, s44
	s_addc_u32 s30, s41, s45
	s_lshl_b64 s[40:41], s[46:47], 2
	s_add_u32 s40, s26, s40
	s_addc_u32 s41, s30, s41
	v_lshl_add_u64 v[6:7], s[40:41], 0, v[0:1]
	v_mul_lo_u32 v4, s43, v34
	v_mul_lo_u32 v5, s42, v37
	v_mad_u64_u32 v[2:3], s[40:41], s42, v34, 0
	v_add3_u32 v3, v3, v5, v4
	v_lshl_add_u64 v[2:3], v[2:3], 2, v[6:7]
	global_load_dwordx4 v[2:5], v[2:3], off nt
	v_mov_b32_e32 v100, 1.0
	s_cmp_lg_u64 s[38:39], 0
	v_add_u32_e32 v10, s36, v34
	s_cselect_b64 s[40:41], -1, 0
	s_cmp_eq_u64 s[38:39], 0
	v_ashrrev_i32_e32 v11, 31, v10
	s_cbranch_scc1 .LBB0_535
	v_lshl_add_u64 v[8:9], v[10:11], 2, s[38:39]
	global_load_dword v100, v[8:9], off
.LBB0_535:
	v_mul_lo_u32 v12, s43, v38
	v_mul_lo_u32 v13, s42, v39
	v_mad_u64_u32 v[8:9], s[42:43], s42, v38, 0
	v_add3_u32 v9, v9, v13, v12
	v_lshl_add_u64 v[6:7], v[8:9], 2, v[6:7]
	global_load_dwordx4 v[6:9], v[6:7], off nt
	v_mov_b32_e32 v102, 1.0
	s_andn2_b64 vcc, exec, s[40:41]
	s_cbranch_vccnz .LBB0_537
	v_lshl_add_u64 v[10:11], v[10:11], 2, s[38:39]
	global_load_dword v102, v[10:11], off offset:128

; __device__ void phase_prep(const Params& p, LAS unsigned char* lds) {
;     ...
;         for (int q = 0; q < 4; ++q) {
;             const int idx = grp * 4 + q;
;             const int l = idx / 3520; int r = idx % 3520;
;             int kt, nt;
;             if (r < 1024) { gs[q] = p.in[8] + l * DM; src[q] = p.in[9] + (size_t)l * DM * DIN; ldns[q] = DIN; Ks[q] = DM; dst[q] = (bf16_t*)(p.ws + W_WIN) + (size_t)l * NPROJ * DM; nt = r % 64; kt = r / 64; }
;             else if (r < 1408) { r -= 1024; gs[q] = nullptr; src[q] = p.in[24] + (size_t)l * DMIX * DM; ldns[q] = DM; Ks[q] = DMIX; dst[q] = (bf16_t*)(p.ws + W_WOUT) + (size_t)l * DM * DMIX; nt = r % 16; kt = r / 16; }
;             else if (r < 2816) { r -= 1408; gs[q] = p.in[25] + l * DM; src[q] = p.in[26] + (size_t)l * DM * DGU; ldns[q] = DGU; Ks[q] = DM; dst[q] = (bf16_t*)(p.ws + W_WUP) + (size_t)l * DGU * DM; nt = r % 88; kt = r / 88; }
;             else { r -= 2816; gs[q] = nullptr; src[q] = p.in[29] + (size_t)l * DFF * DM; ldns[q] = DM; Ks[q] = DFF; dst[q] = (bf16_t*)(p.ws + W_WDOWN) + (size_t)l * DM * DFF; nt = r % 16; kt = r / 16; }
;             int drow = nt * 64;
;             if (ldns[q] == DGU) { const int f = drow < DFF ? drow : drow - DFF; drow = 256 * (f >> 7) + (f & 127) + (drow < DFF ? 0 : 128); }
;             src[q] += (size_t)(kt * 64) * ldns[q] + nt * 64; dst[q] += (size_t)drow * Ks[q] + kt * 64;
; #pragma unroll
;             for (int ps = 0; ps < 2; ++ps) { v[q][ps] = __builtin_nontemporal_load((const f32x4*)(src[q] + (size_t)((tid >> 4) + ps * 32) * ldns[q] + (tid & 15) * 4)); if (gs[q]) v[q][ps] = v[q][ps] * gs[q][kt * 64 + (tid >> 4) + ps * 32]; }
;         }
.LBB0_541:
	s_lshl_b32 s42, s30, 6
	s_ashr_i32 s43, s42, 31
	s_mul_i32 s30, s48, s43
	s_mul_hi_u32 s50, s48, s42
	s_add_i32 s30, s50, s30
	s_mul_i32 s50, s49, s42
	s_add_i32 s51, s30, s50
	s_mul_i32 s50, s48, s42
	s_ashr_i32 s53, s52, 31
	s_lshl_b64 s[50:51], s[50:51], 2
	s_add_u32 s30, s46, s50
	s_addc_u32 s50, s47, s51
	s_lshl_b64 s[46:47], s[52:53], 2
	s_add_u32 s46, s30, s46
	s_addc_u32 s47, s50, s47
	v_lshl_add_u64 v[14:15], s[46:47], 0, v[0:1]
	v_mul_lo_u32 v12, s49, v34
	v_mul_lo_u32 v13, s48, v37
	v_mad_u64_u32 v[10:11], s[46:47], s48, v34, 0
	v_add3_u32 v11, v11, v13, v12
	v_lshl_add_u64 v[10:11], v[10:11], 2, v[14:15]
	global_load_dwordx4 v[10:13], v[10:11], off nt
	v_mov_b32_e32 v104, 1.0
	s_cmp_lg_u64 s[44:45], 0
	v_add_u32_e32 v18, s42, v34
	s_cselect_b64 s[46:47], -1, 0
	s_cmp_eq_u64 s[44:45], 0
	v_ashrrev_i32_e32 v19, 31, v18
	s_cbranch_scc1 .LBB0_543
	v_lshl_add_u64 v[16:17], v[18:19], 2, s[44:45]
	global_load_dword v104, v[16:17], off
.LBB0_543:
	v_mul_lo_u32 v20, s49, v38
	v_mul_lo_u32 v21, s48, v39
	v_mad_u64_u32 v[16:17], s[48:49], s48, v38, 0
	v_add3_u32 v17, v17, v21, v20
	v_lshl_add_u64 v[14:15], v[16:17], 2, v[14:15]
	global_load_dwordx4 v[14:17], v[14:15], off nt
	v_mov_b32_e32 v106, 1.0
	s_andn2_b64 vcc, exec, s[46:47]
	s_cbranch_vccnz .LBB0_545
	v_lshl_add_u64 v[18:19], v[18:19], 2, s[44:45]
	global_load_dword v106, v[18:19], off offset:128

; __device__ void phase_prep(const Params& p, LAS unsigned char* lds) {
;     ...
;         for (int q = 0; q < 4; ++q) {
;             const int idx = grp * 4 + q;
;             const int l = idx / 3520; int r = idx % 3520;
;             int kt, nt;
;             if (r < 1024) { gs[q] = p.in[8] + l * DM; src[q] = p.in[9] + (size_t)l * DM * DIN; ldns[q] = DIN; Ks[q] = DM; dst[q] = (bf16_t*)(p.ws + W_WIN) + (size_t)l * NPROJ * DM; nt = r % 64; kt = r / 64; }
;             else if (r < 1408) { r -= 1024; gs[q] = nullptr; src[q] = p.in[24] + (size_t)l * DMIX * DM; ldns[q] = DM; Ks[q] = DMIX; dst[q] = (bf16_t*)(p.ws + W_WOUT) + (size_t)l * DM * DMIX; nt = r % 16; kt = r / 16; }
;             else if (r < 2816) { r -= 1408; gs[q] = p.in[25] + l * DM; src[q] = p.in[26] + (size_t)l * DM * DGU; ldns[q] = DGU; Ks[q] = DM; dst[q] = (bf16_t*)(p.ws + W_WUP) + (size_t)l * DGU * DM; nt = r % 88; kt = r / 88; }
;             else { r -= 2816; gs[q] = nullptr; src[q] = p.in[29] + (size_t)l * DFF * DM; ldns[q] = DM; Ks[q] = DFF; dst[q] = (bf16_t*)(p.ws + W_WDOWN) + (size_t)l * DM * DFF; nt = r % 16; kt = r / 16; }
;             int drow = nt * 64;
;             if (ldns[q] == DGU) { const int f = drow < DFF ? drow : drow - DFF; drow = 256 * (f >> 7) + (f & 127) + (drow < DFF ? 0 : 128); }
;             src[q] += (size_t)(kt * 64) * ldns[q] + nt * 64; dst[q] += (size_t)drow * Ks[q] + kt * 64;
; #pragma unroll
;             for (int ps = 0; ps < 2; ++ps) { v[q][ps] = __builtin_nontemporal_load((const f32x4*)(src[q] + (size_t)((tid >> 4) + ps * 32) * ldns[q] + (tid & 15) * 4)); if (gs[q]) v[q][ps] = v[q][ps] * gs[q][kt * 64 + (tid >> 4) + ps * 32]; }
;         }
.LBB0_549:
	s_lshl_b32 s48, s49, 6
	s_ashr_i32 s49, s48, 31
	s_mul_i32 s56, s54, s49
	s_mul_hi_u32 s57, s54, s48
	s_add_i32 s56, s57, s56
	s_mul_i32 s57, s55, s48
	s_add_i32 s57, s56, s57
	s_mul_i32 s56, s54, s48
	s_ashr_i32 s59, s58, 31
	s_lshl_b64 s[56:57], s[56:57], 2
	s_add_u32 s56, s52, s56
	s_addc_u32 s57, s53, s57
	s_lshl_b64 s[52:53], s[58:59], 2
	s_add_u32 s52, s56, s52
	s_addc_u32 s53, s57, s53
	s_waitcnt lgkmcnt(0)
	v_lshl_add_u64 v[22:23], s[52:53], 0, v[0:1]
	v_mul_lo_u32 v20, s55, v34
	v_mul_lo_u32 v21, s54, v37
	v_mad_u64_u32 v[18:19], s[52:53], s54, v34, 0
	v_add3_u32 v19, v19, v21, v20
	v_lshl_add_u64 v[18:19], v[18:19], 2, v[22:23]
	global_load_dwordx4 v[18:21], v[18:19], off nt
	v_mov_b32_e32 v108, 1.0
	s_cmp_lg_u64 s[50:51], 0
	v_add_u32_e32 v26, s48, v34
	s_cselect_b64 s[52:53], -1, 0
	s_cmp_eq_u64 s[50:51], 0
	v_ashrrev_i32_e32 v27, 31, v26
	s_cbranch_scc1 .LBB0_551
	v_lshl_add_u64 v[24:25], v[26:27], 2, s[50:51]
	global_load_dword v108, v[24:25], off
.LBB0_551:
	v_mul_lo_u32 v28, s55, v38
	v_mul_lo_u32 v29, s54, v39
	v_mad_u64_u32 v[24:25], s[54:55], s54, v38, 0
	v_add3_u32 v25, v25, v29, v28
	v_lshl_add_u64 v[22:23], v[24:25], 2, v[22:23]
	global_load_dwordx4 v[22:25], v[22:23], off nt
	v_mov_b32_e32 v110, 1.0
	s_andn2_b64 vcc, exec, s[52:53]
	s_cbranch_vccnz .LBB0_553
	v_lshl_add_u64 v[26:27], v[26:27], 2, s[50:51]
	global_load_dword v110, v[26:27], off offset:128

; __device__ void phase_prep(const Params& p, LAS unsigned char* lds) {
;     ...
;         for (int q = 0; q < 4; ++q) {
;             const int idx = grp * 4 + q;
;             const int l = idx / 3520; int r = idx % 3520;
;             int kt, nt;
;             if (r < 1024) { gs[q] = p.in[8] + l * DM; src[q] = p.in[9] + (size_t)l * DM * DIN; ldns[q] = DIN; Ks[q] = DM; dst[q] = (bf16_t*)(p.ws + W_WIN) + (size_t)l * NPROJ * DM; nt = r % 64; kt = r / 64; }
;             else if (r < 1408) { r -= 1024; gs[q] = nullptr; src[q] = p.in[24] + (size_t)l * DMIX * DM; ldns[q] = DM; Ks[q] = DMIX; dst[q] = (bf16_t*)(p.ws + W_WOUT) + (size_t)l * DM * DMIX; nt = r % 16; kt = r / 16; }
;             else if (r < 2816) { r -= 1408; gs[q] = p.in[25] + l * DM; src[q] = p.in[26] + (size_t)l * DM * DGU; ldns[q] = DGU; Ks[q] = DM; dst[q] = (bf16_t*)(p.ws + W_WUP) + (size_t)l * DGU * DM; nt = r % 88; kt = r / 88; }
;             else { r -= 2816; gs[q] = nullptr; src[q] = p.in[29] + (size_t)l * DFF * DM; ldns[q] = DM; Ks[q] = DFF; dst[q] = (bf16_t*)(p.ws + W_WDOWN) + (size_t)l * DM * DFF; nt = r % 16; kt = r / 16; }
;             int drow = nt * 64;
;             if (ldns[q] == DGU) { const int f = drow < DFF ? drow : drow - DFF; drow = 256 * (f >> 7) + (f & 127) + (drow < DFF ? 0 : 128); }
;             src[q] += (size_t)(kt * 64) * ldns[q] + nt * 64; dst[q] += (size_t)drow * Ks[q] + kt * 64;
; #pragma unroll
;             for (int ps = 0; ps < 2; ++ps) { v[q][ps] = __builtin_nontemporal_load((const f32x4*)(src[q] + (size_t)((tid >> 4) + ps * 32) * ldns[q] + (tid & 15) * 4)); if (gs[q]) v[q][ps] = v[q][ps] * gs[q][kt * 64 + (tid >> 4) + ps * 32]; }
;         }
.LBB0_557:
	s_lshl_b32 s58, s59, 6
	s_ashr_i32 s59, s58, 31
	s_mul_i32 s63, s60, s59
	s_mul_hi_u32 s65, s60, s58
	s_add_i32 s63, s65, s63
	s_mul_i32 s65, s61, s58
	s_add_i32 s67, s63, s65
	s_mul_i32 s66, s60, s58
	s_ashr_i32 s65, s64, 31
	s_lshl_b64 s[66:67], s[66:67], 2
	s_add_u32 s63, s56, s66
	s_addc_u32 s66, s57, s67
	s_lshl_b64 s[56:57], s[64:65], 2
	s_add_u32 s56, s63, s56
	s_addc_u32 s57, s66, s57
	v_lshl_add_u64 v[30:31], s[56:57], 0, v[0:1]
	v_mul_lo_u32 v28, s61, v34
	v_mul_lo_u32 v29, s60, v37
	v_mad_u64_u32 v[26:27], s[56:57], s60, v34, 0
	v_add3_u32 v27, v27, v29, v28
	v_lshl_add_u64 v[26:27], v[26:27], 2, v[30:31]
	global_load_dwordx4 v[26:29], v[26:27], off nt
	v_mov_b32_e32 v112, 1.0
	s_cmp_lg_u64 s[54:55], 0
	v_add_u32_e32 v42, s58, v34
	s_cselect_b64 s[56:57], -1, 0
	s_cmp_eq_u64 s[54:55], 0
	v_ashrrev_i32_e32 v43, 31, v42
	s_cbranch_scc1 .LBB0_559
	v_lshl_add_u64 v[32:33], v[42:43], 2, s[54:55]
	global_load_dword v112, v[32:33], off
.LBB0_559:
	v_mul_lo_u32 v41, s61, v38
	v_mul_lo_u32 v47, s60, v39
	v_mad_u64_u32 v[32:33], s[60:61], s60, v38, 0
	v_add3_u32 v33, v33, v47, v41
	v_lshl_add_u64 v[30:31], v[32:33], 2, v[30:31]
	global_load_dwordx4 v[30:33], v[30:31], off nt
	v_mov_b32_e32 v114, 1.0
	s_andn2_b64 vcc, exec, s[56:57]
	s_cbranch_vccnz .LBB0_528
	v_lshl_add_u64 v[42:43], v[42:43], 2, s[54:55]
	global_load_dword v114, v[42:43], off offset:128
	s_branch .LBB0_528
